# speedup vs baseline: 1.0077x; 1.0077x over previous
; #define LAS __attribute__((address_space(3)))
; __device__ __forceinline__ int opaque_tid() { int t; asm volatile("v_mov_b32 %0, %1" : "=v"(t) : "v"(threadIdx.x)); return t; }
; __device__ __forceinline__ int v_rd_base(int lane) { return ((lane & 3) << 3) | (((lane >> 2) & 3) << 6) | (((lane >> 4) & 1) << 5) | (((lane >> 5) & 1) << 8); }
; __device__ __forceinline__ void attn_body256(const bf16_t* __restrict__ Qb, const bf16_t* __restrict__ Kh, const bf16_t* __restrict__ Vh,
;                                              bf16_t* Ob, int seq, unsigned char* lds, float lam, int MODE, bf16_t* Ab, const float* wsub) {
;   const int tid = opaque_tid(), wid = __builtin_amdgcn_readfirstlane(tid >> 6), lane = tid & 63, r32 = lane & 31, hi = lane >> 5;
;   LAS unsigned char* ldsl = (LAS unsigned char*)lds;
;   float* ws = (float*)(lds + A2_WS) + wid * 64; float* li_l = ws; float* al_l = ws + 32;
;   unsigned koff[2], voff[4];
; #pragma unroll
;   for (int i = 0; i < 2; ++i) { const int o = i * 8192 + tid * 16; const int row = o >> 8; const int colB = (o & 255) ^ ((row & 7) << 4);
;     koff[i] = (unsigned)(row * LDK + (colB >> 1));
;     const int sub = o >> 9, kk = (sub >> 2) * 8 + ((o & 511) >> 6), c = (sub & 3) * 32 + (((o & 511) >> 1) & 31);
;     const int k = (kk & ~0xC) | ((kk & 4) << 1) | ((kk & 8) >> 1);
;     voff[i] = (unsigned)(k * LDK + c); voff[2 + i] = (unsigned)(k * LDK + 128 + c); }
;     ...
;   const int NT = seq / KVBLK;
;   A2_DMA(0, 0); A2_DMA(1, 1);
;   float m_reg = -1e30f, l_reg = 0; f32x16 o[8] = {}; bf16x8 qr[8];
;   const bf16_t* Qw = Qb + (long)(wid * QBLK + r32) * LDQ + hi * 8;
; #pragma unroll
;   for (int d0 = 0; d0 < 8; ++d0) qr[d0] = *reinterpret_cast<const bf16x8*>(Qw + d0 * 16);
;   const int vb0 = (int)(uintptr_t)lds + v_rd_base(lane);
;   asm volatile("s_waitcnt vmcnt(0)" ::: "memory"); __syncthreads();
.LBB0_669:
	s_and_b32 s2, s18, 1
	s_lshl_b64 s[10:11], s[62:63], 11
	s_lshl_b64 s[6:7], s[62:63], 12
	s_add_u32 s9, s96, s6
	s_addc_u32 s12, s97, s7
	s_lshl_b32 s16, s8, 8
	s_lshl_b32 s6, s2, 7
	s_or_b32 s6, s16, s6
	s_ashr_i32 s7, s6, 31
	s_lshl_b64 s[14:15], s[6:7], 1
	s_add_u32 s6, s9, s14
	s_addc_u32 s7, s12, s15
	s_lshl_b64 s[8:9], s[0:1], 1
	s_add_u32 s0, s60, s8
	s_addc_u32 s1, s53, s9
	s_add_u32 s12, s0, s14
	s_addc_u32 s13, s1, s15
	v_mov_b32 v16, v231
	v_lshrrev_b32_e32 v245, 7, v231
	v_lshlrev_b32_e32 v245, 3, v245
	v_bfe_u32 v244, v231, 1, 3
	v_add_u32_e32 v245, v245, v244
	v_lshlrev_b32_e32 v245, 11, v245
	v_bfe_u32 v244, v231, 4, 3
	v_lshl_add_u32 v245, v244, 4, v245
	v_and_b32_e32 v244, 1, v231
	v_lshl_add_u32 v245, v244, 3, v245
	v_lshrrev_b32_e32 v239, 4, v231
	v_and_b32_e32 v244, 15, v239
	v_and_b32_e32 v242, 15, v231
	v_xor_b32_e32 v242, v242, v244
	v_lshlrev_b32_e32 v242, 3, v242
	v_lshl_add_u32 v239, v239, 11, v242
	s_add_u32 s20, s61, s8
	v_lshlrev_b32_e32 v17, 4, v16
	v_add_u32_e32 v6, 0x2000, v17
	s_addc_u32 s21, s68, s9
	s_ashr_i32 s17, s16, 31
	v_ashrrev_i32_e32 v8, 8, v6
	s_lshl_b64 s[0:1], s[16:17], 1
	v_and_b32_e32 v3, 0xf0, v17
	v_lshlrev_b32_e32 v6, 4, v8
	s_movk_i32 s26, 0x70
	s_add_u32 s16, s20, s0
	v_lshrrev_b32_e32 v0, 1, v16
	v_ashrrev_i32_e32 v2, 4, v16
	v_bitop3_b32 v3, v6, v3, s26 bitop3:0x6c
	s_addc_u32 s17, s21, s1
	v_readfirstlane_b32 s20, v16
	v_and_b32_e32 v22, 8, v0
	v_and_b32_e32 v0, 0x70, v16
	s_movk_i32 s21, 0xf0
	v_lshrrev_b32_e32 v4, 1, v2
	v_lshrrev_b32_e32 v3, 1, v3
	s_ashr_i32 s23, s20, 6
	v_bfe_u32 v18, v16, 2, 2
	v_lshlrev_b32_e32 v20, 3, v16
	v_bitop3_b32 v0, v17, v0, s21 bitop3:0x6c
	v_and_b32_e32 v4, 4, v4
	v_lshl_or_b32 v6, v8, 11, v3
	v_add_u32_e32 v6, 0x10000, v239
	v_and_b32_e32 v3, 0x1ffff0, v8
	v_lshrrev_b32_e32 v8, 1, v8
	v_and_b32_e32 v19, 0x60, v16
	v_and_b32_e32 v21, 24, v20
	v_or_b32_e32 v7, v22, v18
	v_lshrrev_b32_e32 v0, 1, v0
	v_and_or_b32 v23, v2, -16, v4
	v_and_b32_e32 v8, 4, v8
	s_lshl_b32 s21, s23, 10
	v_or_b32_e32 v5, v21, v19
	v_lshl_or_b32 v0, v2, 11, v0
	v_mov_b32_e32 v0, v239
	v_or_b32_e32 v2, v7, v23
	v_or3_b32 v3, v3, v8, v7
	s_add_i32 s21, s21, 0
	v_lshl_or_b32 v2, v2, 11, v5
	v_mov_b32_e32 v2, v245
	v_lshlrev_b32_e32 v24, 11, v3
	s_add_i32 s22, s21, 0x10000
	v_lshlrev_b64 v[12:13], 1, v[0:1]
	v_mov_b32_e32 v3, v1
	v_or_b32_e32 v4, 0x80, v2
	v_lshl_add_u64 v[14:15], s[12:13], 0, v[12:13]
	s_mov_b32 m0, s22
	v_lshlrev_b64 v[2:3], 1, v[2:3]
	s_add_i32 s24, s21, 0x4000
	global_load_lds_dwordx4 v[14:15], off
	v_lshl_add_u64 v[14:15], s[16:17], 0, v[2:3]
	s_mov_b32 m0, s21
	s_mov_b64 s[30:31], 0x100
	v_mov_b32_e32 v7, v1
	s_and_b32 s20, s20, 0x3fffffc0
	v_or_b32_e32 v8, v24, v5
	v_add_u32_e32 v8, 0x10000, v245
	global_load_lds_dwordx4 v[14:15], off
	v_lshl_add_u64 v[14:15], v[14:15], 0, s[30:31]
	s_mov_b32 m0, s24
	v_lshlrev_b64 v[6:7], 1, v[6:7]
	v_mov_b32_e32 v9, v1
	s_lshl_b32 s20, s20, 2
	v_or_b32_e32 v10, 0x80, v8
	global_load_lds_dwordx4 v[14:15], off
	v_lshl_add_u64 v[14:15], s[12:13], 0, v[6:7]
	s_add_i32 m0, s21, 0x12000
	v_lshlrev_b64 v[8:9], 1, v[8:9]
	s_add_i32 s20, s20, 0
	global_load_lds_dwordx4 v[14:15], off
	v_lshl_add_u64 v[14:15], s[16:17], 0, v[8:9]
	s_add_i32 m0, s21, 0x2000
	s_add_i32 s20, s20, 0x18000
	global_load_lds_dwordx4 v[14:15], off
	s_add_i32 m0, s21, 0x6000
	s_add_u32 s12, s12, 0x40000
	s_addc_u32 s13, s13, 0
	v_lshl_add_u64 v[14:15], v[14:15], 0, s[30:31]
	s_add_u32 s16, s16, 0x40000
	global_load_lds_dwordx4 v[14:15], off
	s_addc_u32 s17, s17, 0
	s_add_i32 m0, s21, 0x14000
	s_add_i32 s24, s21, 0x8000
	v_lshl_add_u64 v[14:15], s[12:13], 0, v[12:13]
	v_mov_b32_e32 v5, v1
	s_add_i32 s25, s21, 0xc000
	global_load_lds_dwordx4 v[14:15], off
	v_lshl_add_u64 v[2:3], s[16:17], 0, v[2:3]
	s_mov_b32 m0, s24
	v_mov_b32_e32 v11, v1
	global_load_lds_dwordx4 v[2:3], off
	v_lshl_add_u64 v[2:3], v[4:5], 1, s[16:17]
	s_mov_b32 m0, s25
	v_and_b32_e32 v228, 31, v16
	global_load_lds_dwordx4 v[2:3], off
	v_lshl_add_u64 v[2:3], s[12:13], 0, v[6:7]
	s_add_i32 m0, s21, 0x16000
	s_lshl_b32 s12, s23, 5
	global_load_lds_dwordx4 v[2:3], off
	v_lshl_add_u64 v[2:3], s[16:17], 0, v[8:9]
	s_add_i32 m0, s21, 0xa000
	v_bfe_u32 v229, v16, 5, 1
	global_load_lds_dwordx4 v[2:3], off
	v_lshl_add_u64 v[2:3], v[10:11], 1, s[16:17]
	s_add_i32 m0, s21, 0xe000
	v_lshlrev_b32_e32 v0, 4, v229
	global_load_lds_dwordx4 v[2:3], off
	v_and_b32_e32 v2, 15, v231
	v_or_b32_e32 v2, s12, v2
	v_mov_b32_e32 v3, 0
	v_lshlrev_b64 v[2:3], 12, v[2:3]
	v_lshl_add_u64 v[2:3], s[6:7], 0, v[2:3]
	v_bfe_u32 v194, v231, 4, 2
	v_lshlrev_b32_e32 v194, 4, v194
	v_mov_b32_e32 v195, 0
	v_lshl_add_u64 v[2:3], v[2:3], 0, v[194:195]
	global_load_dwordx4 v[162:165], v[2:3], off
	global_load_dwordx4 v[166:169], v[2:3], off offset:64
	global_load_dwordx4 v[170:173], v[2:3], off offset:128
	global_load_dwordx4 v[174:177], v[2:3], off offset:192
	v_mov_b32_e32 v194, 0x10000
	v_lshl_add_u64 v[2:3], v[2:3], 0, v[194:195]
	global_load_dwordx4 v[178:181], v[2:3], off
	global_load_dwordx4 v[182:185], v[2:3], off offset:64
	global_load_dwordx4 v[186:189], v[2:3], off offset:128
	global_load_dwordx4 v[190:193], v[2:3], off offset:192
	v_and_b32_e32 v8, 0x70, v17
	s_movk_i32 s6, 0x60
	v_bitop3_b32 v236, v0, v8, s6 bitop3:0x36
	s_movk_i32 s6, 0x80
	v_bitop3_b32 v237, v0, v8, s6 bitop3:0x36
	s_movk_i32 s6, 0xa0
	v_bitop3_b32 v240, v0, v8, s6 bitop3:0x36
	s_movk_i32 s6, 0xc0
	s_cmp_lg_u32 0, -1
	v_and_b32_e32 v2, 63, v16
	v_lshlrev_b32_e32 v3, 1, v16
	v_and_b32_e32 v4, 0x118, v20
	v_bitop3_b32 v241, v0, v8, s6 bitop3:0x36
	s_movk_i32 s6, 0xe0
	s_cselect_b32 s16, 0, 0
	s_lshl_b32 s23, s19, 18
	v_and_b32_e32 v5, 0xc0, v17
	v_bitop3_b32 v247, v0, v8, s6 bitop3:0x36
	v_cmp_gt_u32_e64 s[6:7], 32, v2
	v_and_or_b32 v2, v3, 32, v4
	s_add_u32 s14, s8, s14
	v_add3_u32 v248, v5, s16, v2
	s_addc_u32 s15, s9, s15
	v_readlane_b32 s16, v254, 41
	s_add_u32 s14, s16, s14
	v_readlane_b32 s16, v254, 42
	s_addc_u32 s15, s16, s15
	s_add_u32 s8, s8, s0
	s_addc_u32 s9, s9, s1
	v_or3_b32 v2, v23, v22, v18
	v_lshlrev_b32_e32 v2, 11, v2
	s_add_u32 s8, s88, s8
	v_or3_b32 v2, v2, v19, v21
	v_mov_b32_e32 v2, v245
	v_mov_b32_e32 v3, v1
	s_addc_u32 s9, s89, s9
	s_waitcnt vmcnt(0)
; #define LAS __attribute__((address_space(3)))
; __device__ __forceinline__ int opaque_tid() { int t; asm volatile("v_mov_b32 %0, %1" : "=v"(t) : "v"(threadIdx.x)); return t; }
; __device__ __forceinline__ int v_rd_base(int lane) { return ((lane & 3) << 3) | (((lane >> 2) & 3) << 6) | (((lane >> 4) & 1) << 5) | (((lane >> 5) & 1) << 8); }
; __device__ __forceinline__ void attn_body256(const bf16_t* __restrict__ Qb, const bf16_t* __restrict__ Kh, const bf16_t* __restrict__ Vh,
;                                              bf16_t* Ob, int seq, unsigned char* lds, float lam, int MODE, bf16_t* Ab, const float* wsub) {
;   const int tid = opaque_tid(), wid = __builtin_amdgcn_readfirstlane(tid >> 6), lane = tid & 63, r32 = lane & 31, hi = lane >> 5;
;   LAS unsigned char* ldsl = (LAS unsigned char*)lds;
;   float* ws = (float*)(lds + A2_WS) + wid * 64; float* li_l = ws; float* al_l = ws + 32;
;   unsigned koff[2], voff[4];
; #pragma unroll
;   for (int i = 0; i < 2; ++i) { const int o = i * 8192 + tid * 16; const int row = o >> 8; const int colB = (o & 255) ^ ((row & 7) << 4);
;     koff[i] = (unsigned)(row * LDK + (colB >> 1));
;     const int sub = o >> 9, kk = (sub >> 2) * 8 + ((o & 511) >> 6), c = (sub & 3) * 32 + (((o & 511) >> 1) & 31);
;     const int k = (kk & ~0xC) | ((kk & 4) << 1) | ((kk & 8) >> 1);
;     voff[i] = (unsigned)(k * LDK + c); voff[2 + i] = (unsigned)(k * LDK + 128 + c); }
;     ...
;   const int NT = seq / KVBLK;
;   A2_DMA(0, 0); A2_DMA(1, 1);
;   float m_reg = -1e30f, l_reg = 0; f32x16 o[8] = {}; bf16x8 qr[8];
;   const bf16_t* Qw = Qb + (long)(wid * QBLK + r32) * LDQ + hi * 8;
; #pragma unroll
;   for (int d0 = 0; d0 < 8; ++d0) qr[d0] = *reinterpret_cast<const bf16x8*>(Qw + d0 * 16);
;   const int vb0 = (int)(uintptr_t)lds + v_rd_base(lane);
;   asm volatile("s_waitcnt vmcnt(0)" ::: "memory"); __syncthreads();
	v_bitop3_b32 v232, v0, v17, s26 bitop3:0x78
	v_lshl_add_u64 v[224:225], v[2:3], 1, s[8:9]
	v_or3_b32 v2, v24, v19, v21
	v_add_u32_e32 v2, 0x10000, v245
	v_mov_b32_e32 v16, v1
	v_mov_b32_e32 v17, v1
	v_bitop3_b32 v233, v0, v8, 32 bitop3:0x36
	v_bitop3_b32 v234, v0, v8, 64 bitop3:0x36
	v_lshl_add_u64 v[220:221], s[14:15], 0, v[12:13]
	v_lshl_add_u64 v[222:223], s[14:15], 0, v[6:7]
	v_lshl_add_u64 v[226:227], v[2:3], 1, s[8:9]
	v_mov_b32_e32 v2, v1
	v_mov_b32_e32 v4, v1
	v_mov_b32_e32 v5, v1
	v_mov_b32_e32 v6, v1
	v_mov_b32_e32 v7, v1
	v_mov_b32_e32 v8, v1
	v_mov_b32_e32 v9, v1
	v_mov_b32_e32 v10, v1
	v_mov_b32_e32 v12, v1
	v_mov_b32_e32 v13, v1
	v_mov_b32_e32 v14, v1
	v_mov_b32_e32 v15, v1
	v_mov_b64_e32 v[128:129], v[16:17]
	v_mov_b64_e32 v[112:113], v[16:17]
	v_mov_b64_e32 v[96:97], v[16:17]
	v_mov_b64_e32 v[80:81], v[16:17]
	v_mov_b64_e32 v[64:65], v[16:17]
	v_mov_b64_e32 v[48:49], v[16:17]
	v_mov_b64_e32 v[32:33], v[16:17]
	s_mov_b32 s13, 2
	v_lshlrev_b32_e32 v230, 8, v228
	v_lshl_add_u32 v238, v228, 2, s20
	v_mov_b32_e32 v250, 0
	v_mov_b32_e32 v249, 0xf149f2ca
	s_mov_b64 s[14:15], 0
	v_mov_b64_e32 v[126:127], v[14:15]
	v_mov_b64_e32 v[124:125], v[12:13]
	v_mov_b64_e32 v[122:123], v[10:11]
	v_mov_b64_e32 v[120:121], v[8:9]
	v_mov_b64_e32 v[118:119], v[6:7]
	v_mov_b64_e32 v[116:117], v[4:5]
	v_mov_b64_e32 v[114:115], v[2:3]
	v_mov_b64_e32 v[110:111], v[14:15]
	v_mov_b64_e32 v[108:109], v[12:13]
	v_mov_b64_e32 v[106:107], v[10:11]
	v_mov_b64_e32 v[104:105], v[8:9]
	v_mov_b64_e32 v[102:103], v[6:7]
	v_mov_b64_e32 v[100:101], v[4:5]
	v_mov_b64_e32 v[98:99], v[2:3]
	v_mov_b64_e32 v[94:95], v[14:15]
	v_mov_b64_e32 v[92:93], v[12:13]
	v_mov_b64_e32 v[90:91], v[10:11]
	v_mov_b64_e32 v[88:89], v[8:9]
	v_mov_b64_e32 v[86:87], v[6:7]
	v_mov_b64_e32 v[84:85], v[4:5]
	v_mov_b64_e32 v[82:83], v[2:3]
	v_mov_b64_e32 v[78:79], v[14:15]
	v_mov_b64_e32 v[76:77], v[12:13]
	v_mov_b64_e32 v[74:75], v[10:11]
	v_mov_b64_e32 v[72:73], v[8:9]
	v_mov_b64_e32 v[70:71], v[6:7]
	v_mov_b64_e32 v[68:69], v[4:5]
	v_mov_b64_e32 v[66:67], v[2:3]
	v_mov_b64_e32 v[62:63], v[14:15]
	v_mov_b64_e32 v[60:61], v[12:13]
	v_mov_b64_e32 v[58:59], v[10:11]
	v_mov_b64_e32 v[56:57], v[8:9]
	v_mov_b64_e32 v[54:55], v[6:7]
	v_mov_b64_e32 v[52:53], v[4:5]
	v_mov_b64_e32 v[50:51], v[2:3]
	v_mov_b64_e32 v[46:47], v[14:15]
	v_mov_b64_e32 v[44:45], v[12:13]
	v_mov_b64_e32 v[42:43], v[10:11]
	v_mov_b64_e32 v[40:41], v[8:9]
	v_mov_b64_e32 v[38:39], v[6:7]
	v_mov_b64_e32 v[36:37], v[4:5]
	v_mov_b64_e32 v[34:35], v[2:3]
	v_mov_b64_e32 v[30:31], v[14:15]
	v_mov_b64_e32 v[28:29], v[12:13]
	v_mov_b64_e32 v[26:27], v[10:11]
	v_mov_b64_e32 v[24:25], v[8:9]
	v_mov_b64_e32 v[22:23], v[6:7]
	v_mov_b64_e32 v[20:21], v[4:5]
	v_mov_b64_e32 v[18:19], v[2:3]
	v_and_b32_e32 v237, 15, v231
	v_bfe_u32 v240, v231, 4, 2
	v_add_u32_e32 v247, 0, v240
	v_xor_b32_e32 v247, v247, v237
	v_lshlrev_b32_e32 v247, 4, v247
	v_lshl_add_u32 v232, v237, 8, v247
	v_add_u32_e32 v247, 4, v240
	v_xor_b32_e32 v247, v247, v237
	v_lshlrev_b32_e32 v247, 4, v247
	v_lshl_add_u32 v233, v237, 8, v247
	v_add_u32_e32 v247, 8, v240
	v_xor_b32_e32 v247, v247, v237
	v_lshlrev_b32_e32 v247, 4, v247
	v_lshl_add_u32 v242, v237, 8, v247
	v_add_u32_e32 v247, 12, v240
	v_xor_b32_e32 v247, v247, v237
	v_lshlrev_b32_e32 v247, 4, v247
	v_lshl_add_u32 v243, v237, 8, v247
	v_and_b32_e32 v247, 1, v240
	v_lshlrev_b32_e32 v248, 7, v247
	v_lshrrev_b32_e32 v247, 1, v240
	v_lshl_add_u32 v248, v247, 11, v248
	v_bfe_u32 v247, v231, 2, 2
	v_lshl_add_u32 v248, v247, 5, v248
	v_and_b32_e32 v247, 3, v231
	v_lshl_add_u32 v248, v247, 3, v248
	v_mov_b32_e32 v249, 0xf149f2ca
	v_mov_b32_e32 v246, 0xf149f2ca
	v_mov_b32_e32 v250, 0
	v_mov_b32_e32 v234, 0
	v_mul_f32_e32 v251, 0xbe0293ee, v249
	v_mul_f32_e32 v238, 0xbe0293ee, v246
	s_movk_i32 s62, 0x7fff
	s_waitcnt vmcnt(0) lgkmcnt(0)
	s_barrier
	s_mov_b32 s98, 0
	s_mov_b32 s99, 0x8000
	s_mov_b32 s100, 0x19000
	s_cmpk_ge_u32 s21, 0x1000
	s_cbranch_scc1 .Lat_y_qk
	s_mov_b32 s9, 0x10000
	v_add_u32_e32 v230, s9, v232
	v_add_u32_e32 v247, s9, v233
	v_add_u32_e32 v239, s9, v242
	v_add_u32_e32 v245, s9, v243
	ds_read_b128 v[194:197], v230
	ds_read_b128 v[198:201], v230 offset:4096
	ds_read_b128 v[202:205], v230 offset:8192
	ds_read_b128 v[206:209], v230 offset:12288
	ds_read_b128 v[210:213], v247
	ds_read_b128 v[214:217], v247 offset:4096
; __device__ __forceinline__ void partialSM(f32x16& p0, f32x16& p1, float& m_reg, float& mn, float& alpha) {
;   constexpr float C = SCALE * 1.4426950408889634f;
;   float pmax = p0[0]; for (int r = 1; r < 16; ++r) pmax = fmaxf(pmax, p0[r]); for (int r = 0; r < 16; ++r) pmax = fmaxf(pmax, p1[r]);
;   { auto rr = __builtin_amdgcn_permlane32_swap(__float_as_uint(pmax), __float_as_uint(pmax), false, false);
;     pmax = fmaxf(__uint_as_float(rr[0]), __uint_as_float(rr[1])); }
;   if (__builtin_expect(__all(pmax - m_reg <= THR / SCALE), 1)) { mn = m_reg; alpha = 1.f; }
;   else { mn = fmaxf(m_reg, pmax); alpha = __builtin_amdgcn_exp2f((m_reg - mn) * C); m_reg = mn; }
; __device__ __forceinline__ void qkt(f32x16& p0, f32x16& p1, const bf16_t* Ks, const bf16x8* qr, int r32, int hi) {
;   p0 = f32x16{}; p1 = f32x16{};
;   for (int d0 = 0; d0 < 8; ++d0) { int cb = (d0 * 16 + hi * 8) * 2;
;     bf16x8 b0 = *reinterpret_cast<const bf16x8*>((const char*)Ks + KSWZ(r32, cb));
;     bf16x8 b1 = *reinterpret_cast<const bf16x8*>((const char*)Ks + KSWZ(32 + r32, cb));
;     p0 = __builtin_amdgcn_mfma_f32_32x32x16_bf16(b0, qr[d0], p0, 0, 0, 0);
;     p1 = __builtin_amdgcn_mfma_f32_32x32x16_bf16(b1, qr[d0], p1, 0, 0, 0); }
.Lat_x_top:
	s_add_i32 s8, s13, -2
	s_and_b32 s25, s8, 1
	s_lshl_b32 s24, s25, 14
	s_setprio 1
	s_waitcnt lgkmcnt(5)
	v_mfma_f32_16x16x32_bf16 v[130:133], v[194:197], v[162:165], 0
	v_mfma_f32_16x16x32_bf16 v[134:137], v[194:197], v[178:181], 0
	ds_read_b128 v[194:197], v247 offset:8192
	s_waitcnt lgkmcnt(5)
	v_mfma_f32_16x16x32_bf16 v[138:141], v[198:201], v[162:165], 0
	v_mfma_f32_16x16x32_bf16 v[142:145], v[198:201], v[178:181], 0
	ds_read_b128 v[198:201], v247 offset:12288
	s_waitcnt lgkmcnt(5)
	v_mfma_f32_16x16x32_bf16 v[146:149], v[202:205], v[162:165], 0
	v_mfma_f32_16x16x32_bf16 v[150:153], v[202:205], v[178:181], 0
	ds_read_b128 v[202:205], v239
	s_waitcnt lgkmcnt(5)
	v_mfma_f32_16x16x32_bf16 v[154:157], v[206:209], v[162:165], 0
	v_mfma_f32_16x16x32_bf16 v[158:161], v[206:209], v[178:181], 0
	ds_read_b128 v[206:209], v239 offset:4096
	s_waitcnt lgkmcnt(5)
	v_mfma_f32_16x16x32_bf16 v[130:133], v[210:213], v[166:169], v[130:133]
	v_mfma_f32_16x16x32_bf16 v[134:137], v[210:213], v[182:185], v[134:137]
	ds_read_b128 v[210:213], v239 offset:8192
	s_waitcnt lgkmcnt(5)
	v_mfma_f32_16x16x32_bf16 v[138:141], v[214:217], v[166:169], v[138:141]
	v_mfma_f32_16x16x32_bf16 v[142:145], v[214:217], v[182:185], v[142:145]
	ds_read_b128 v[214:217], v239 offset:12288
	s_waitcnt lgkmcnt(5)
	v_mfma_f32_16x16x32_bf16 v[146:149], v[194:197], v[166:169], v[146:149]
	v_mfma_f32_16x16x32_bf16 v[150:153], v[194:197], v[182:185], v[150:153]
	ds_read_b128 v[194:197], v245
	s_waitcnt lgkmcnt(5)
	v_mfma_f32_16x16x32_bf16 v[154:157], v[198:201], v[166:169], v[154:157]
	v_mfma_f32_16x16x32_bf16 v[158:161], v[198:201], v[182:185], v[158:161]
	ds_read_b128 v[198:201], v245 offset:4096
	s_waitcnt lgkmcnt(5)
	v_mfma_f32_16x16x32_bf16 v[130:133], v[202:205], v[170:173], v[130:133]
	v_mfma_f32_16x16x32_bf16 v[134:137], v[202:205], v[186:189], v[134:137]
	ds_read_b128 v[202:205], v245 offset:8192
	s_waitcnt lgkmcnt(5)
	v_mfma_f32_16x16x32_bf16 v[138:141], v[206:209], v[170:173], v[138:141]
	v_mfma_f32_16x16x32_bf16 v[142:145], v[206:209], v[186:189], v[142:145]
	ds_read_b128 v[206:209], v245 offset:12288
	s_waitcnt lgkmcnt(5)
	v_mfma_f32_16x16x32_bf16 v[146:149], v[210:213], v[170:173], v[146:149]
	v_mfma_f32_16x16x32_bf16 v[150:153], v[210:213], v[186:189], v[150:153]
	s_waitcnt lgkmcnt(4)
	v_mfma_f32_16x16x32_bf16 v[154:157], v[214:217], v[170:173], v[154:157]
	v_mfma_f32_16x16x32_bf16 v[158:161], v[214:217], v[186:189], v[158:161]
	s_waitcnt lgkmcnt(3)
	v_mfma_f32_16x16x32_bf16 v[130:133], v[194:197], v[174:177], v[130:133]
	v_mfma_f32_16x16x32_bf16 v[134:137], v[194:197], v[190:193], v[134:137]
	s_waitcnt lgkmcnt(2)
	v_mfma_f32_16x16x32_bf16 v[138:141], v[198:201], v[174:177], v[138:141]
	v_mfma_f32_16x16x32_bf16 v[142:145], v[198:201], v[190:193], v[142:145]
	s_waitcnt lgkmcnt(1)
	v_mfma_f32_16x16x32_bf16 v[146:149], v[202:205], v[174:177], v[146:149]
	v_mfma_f32_16x16x32_bf16 v[150:153], v[202:205], v[190:193], v[150:153]
	s_waitcnt lgkmcnt(0)
	v_mfma_f32_16x16x32_bf16 v[154:157], v[206:209], v[174:177], v[154:157]
	v_mfma_f32_16x16x32_bf16 v[158:161], v[206:209], v[190:193], v[158:161]
	s_setprio 0
	s_nop 6
	v_max3_f32 v194, v130, v131, v132
	v_max3_f32 v194, v194, v133, v138
	v_max3_f32 v194, v194, v139, v140
	v_max3_f32 v194, v194, v141, v146
	v_max3_f32 v194, v194, v147, v148
	v_max3_f32 v194, v194, v149, v154
	v_max3_f32 v194, v194, v155, v156
	v_max_f32_e32 v194, v194, v157
	v_max3_f32 v195, v134, v135, v136
	v_max3_f32 v195, v195, v137, v142
	v_max3_f32 v195, v195, v143, v144
	v_max3_f32 v195, v195, v145, v150
	v_max3_f32 v195, v195, v151, v152
	v_max3_f32 v195, v195, v153, v158
	v_max3_f32 v195, v195, v159, v160
	v_max_f32_e32 v195, v195, v161
	v_mov_b32_e32 v196, v194
	v_mov_b32_e32 v197, v195
	s_nop 1
	v_permlane32_swap_b32_e32 v194, v196
	v_permlane32_swap_b32_e32 v195, v197
	v_max_f32_e32 v194, v194, v196
	v_max_f32_e32 v195, v195, v197
	v_mov_b32_e32 v196, v194
	v_mov_b32_e32 v197, v195
	s_nop 1
	v_permlane16_swap_b32_e32 v194, v196
	v_permlane16_swap_b32_e32 v195, v197
	v_max_f32_e32 v194, v194, v196
	v_max_f32_e32 v195, v195, v197
	v_sub_f32_e32 v196, v194, v249
	v_sub_f32_e32 v197, v195, v246
	v_max_f32_e32 v196, v196, v197
	v_cmp_nge_f32_e32 vcc, 0x42b504f3, v196
	s_cbranch_vccz .Lat_x_noresc
; __device__ __forceinline__ int crow(int r, int hi) { return (r & 3) + 8 * (r >> 2) + 4 * hi; }
; __device__ __forceinline__ int crow(int r, int hi) { return (r & 3) + 8 * (r >> 2) + 4 * hi; }
; __device__ __forceinline__ void partialSM(f32x16& p0, f32x16& p1, float& m_reg, float& mn, float& alpha) {
;     ...
;   if (__builtin_expect(__all(pmax - m_reg <= THR / SCALE), 1)) { mn = m_reg; alpha = 1.f; }
;   else { mn = fmaxf(m_reg, pmax); alpha = __builtin_amdgcn_exp2f((m_reg - mn) * C); m_reg = mn; }
; __device__ __forceinline__ void attn_body256(const bf16_t* __restrict__ Qb, const bf16_t* __restrict__ Kh, const bf16_t* __restrict__ Vh,
;                                              bf16_t* Ob, int seq, unsigned char* lds, float lam, int MODE, bf16_t* Ab, const float* wsub) {
;     ...
;     if (__any(alpha < 1.f)) { if (hi == 0) al_l[r32] = alpha; asm volatile("s_waitcnt lgkmcnt(0)" ::: "memory");
; #pragma unroll
;       for (int r = 0; r < 16; ++r) { const float a = al_l[crow(r, hi)];
; #pragma unroll
;         for (int d = 0; d < 8; ++d) o[d][r] *= a; } }
	v_max_f32_e32 v198, v249, v194
	v_max_f32_e32 v199, v246, v195
	v_sub_f32_e32 v196, v249, v198
	v_sub_f32_e32 v197, v246, v199
	v_mul_f32_e32 v196, 0x3e0293ee, v196
	v_mul_f32_e32 v197, 0x3e0293ee, v197
	v_exp_f32_e32 v236, v196
	v_exp_f32_e32 v240, v197
	v_mov_b32_e32 v249, v198
	v_mov_b32_e32 v246, v199
	v_mul_f32_e32 v251, 0xbe0293ee, v198
	v_mul_f32_e32 v238, 0xbe0293ee, v199
	v_mul_f32_e32 v250, v250, v236
	v_mul_f32_e32 v234, v234, v240
	v_pk_mul_f32 v[2:3], v[2:3], v[236:237] op_sel_hi:[1,0]
	v_pk_mul_f32 v[4:5], v[4:5], v[236:237] op_sel_hi:[1,0]
	v_pk_mul_f32 v[6:7], v[6:7], v[240:241] op_sel_hi:[1,0]
	v_pk_mul_f32 v[8:9], v[8:9], v[240:241] op_sel_hi:[1,0]
	v_pk_mul_f32 v[10:11], v[10:11], v[236:237] op_sel_hi:[1,0]
	v_pk_mul_f32 v[12:13], v[12:13], v[236:237] op_sel_hi:[1,0]
	v_pk_mul_f32 v[14:15], v[14:15], v[240:241] op_sel_hi:[1,0]
	v_pk_mul_f32 v[16:17], v[16:17], v[240:241] op_sel_hi:[1,0]
	v_pk_mul_f32 v[114:115], v[114:115], v[236:237] op_sel_hi:[1,0]
	v_pk_mul_f32 v[116:117], v[116:117], v[236:237] op_sel_hi:[1,0]
	v_pk_mul_f32 v[118:119], v[118:119], v[240:241] op_sel_hi:[1,0]
	v_pk_mul_f32 v[120:121], v[120:121], v[240:241] op_sel_hi:[1,0]
	v_pk_mul_f32 v[122:123], v[122:123], v[236:237] op_sel_hi:[1,0]
	v_pk_mul_f32 v[124:125], v[124:125], v[236:237] op_sel_hi:[1,0]
	v_pk_mul_f32 v[126:127], v[126:127], v[240:241] op_sel_hi:[1,0]
	v_pk_mul_f32 v[128:129], v[128:129], v[240:241] op_sel_hi:[1,0]
	v_pk_mul_f32 v[98:99], v[98:99], v[236:237] op_sel_hi:[1,0]
	v_pk_mul_f32 v[100:101], v[100:101], v[236:237] op_sel_hi:[1,0]
	v_pk_mul_f32 v[102:103], v[102:103], v[240:241] op_sel_hi:[1,0]
	v_pk_mul_f32 v[104:105], v[104:105], v[240:241] op_sel_hi:[1,0]
	v_pk_mul_f32 v[106:107], v[106:107], v[236:237] op_sel_hi:[1,0]
	v_pk_mul_f32 v[108:109], v[108:109], v[236:237] op_sel_hi:[1,0]
	v_pk_mul_f32 v[110:111], v[110:111], v[240:241] op_sel_hi:[1,0]
	v_pk_mul_f32 v[112:113], v[112:113], v[240:241] op_sel_hi:[1,0]
	v_pk_mul_f32 v[82:83], v[82:83], v[236:237] op_sel_hi:[1,0]
	v_pk_mul_f32 v[84:85], v[84:85], v[236:237] op_sel_hi:[1,0]
	v_pk_mul_f32 v[86:87], v[86:87], v[240:241] op_sel_hi:[1,0]
	v_pk_mul_f32 v[88:89], v[88:89], v[240:241] op_sel_hi:[1,0]
	v_pk_mul_f32 v[90:91], v[90:91], v[236:237] op_sel_hi:[1,0]
	v_pk_mul_f32 v[92:93], v[92:93], v[236:237] op_sel_hi:[1,0]
	v_pk_mul_f32 v[94:95], v[94:95], v[240:241] op_sel_hi:[1,0]
	v_pk_mul_f32 v[96:97], v[96:97], v[240:241] op_sel_hi:[1,0]
	v_pk_mul_f32 v[66:67], v[66:67], v[236:237] op_sel_hi:[1,0]
	v_pk_mul_f32 v[68:69], v[68:69], v[236:237] op_sel_hi:[1,0]
	v_pk_mul_f32 v[70:71], v[70:71], v[240:241] op_sel_hi:[1,0]
	v_pk_mul_f32 v[72:73], v[72:73], v[240:241] op_sel_hi:[1,0]
	v_pk_mul_f32 v[74:75], v[74:75], v[236:237] op_sel_hi:[1,0]
	v_pk_mul_f32 v[76:77], v[76:77], v[236:237] op_sel_hi:[1,0]
	v_pk_mul_f32 v[78:79], v[78:79], v[240:241] op_sel_hi:[1,0]
	v_pk_mul_f32 v[80:81], v[80:81], v[240:241] op_sel_hi:[1,0]
	v_pk_mul_f32 v[50:51], v[50:51], v[236:237] op_sel_hi:[1,0]
	v_pk_mul_f32 v[52:53], v[52:53], v[236:237] op_sel_hi:[1,0]
	v_pk_mul_f32 v[54:55], v[54:55], v[240:241] op_sel_hi:[1,0]
	v_pk_mul_f32 v[56:57], v[56:57], v[240:241] op_sel_hi:[1,0]
	v_pk_mul_f32 v[58:59], v[58:59], v[236:237] op_sel_hi:[1,0]
	v_pk_mul_f32 v[60:61], v[60:61], v[236:237] op_sel_hi:[1,0]
	v_pk_mul_f32 v[62:63], v[62:63], v[240:241] op_sel_hi:[1,0]
	v_pk_mul_f32 v[64:65], v[64:65], v[240:241] op_sel_hi:[1,0]
	v_pk_mul_f32 v[34:35], v[34:35], v[236:237] op_sel_hi:[1,0]
	v_pk_mul_f32 v[36:37], v[36:37], v[236:237] op_sel_hi:[1,0]
	v_pk_mul_f32 v[38:39], v[38:39], v[240:241] op_sel_hi:[1,0]
	v_pk_mul_f32 v[40:41], v[40:41], v[240:241] op_sel_hi:[1,0]
	v_pk_mul_f32 v[42:43], v[42:43], v[236:237] op_sel_hi:[1,0]
	v_pk_mul_f32 v[44:45], v[44:45], v[236:237] op_sel_hi:[1,0]
	v_pk_mul_f32 v[46:47], v[46:47], v[240:241] op_sel_hi:[1,0]
	v_pk_mul_f32 v[48:49], v[48:49], v[240:241] op_sel_hi:[1,0]
	v_pk_mul_f32 v[18:19], v[18:19], v[236:237] op_sel_hi:[1,0]
	v_pk_mul_f32 v[20:21], v[20:21], v[236:237] op_sel_hi:[1,0]
	v_pk_mul_f32 v[22:23], v[22:23], v[240:241] op_sel_hi:[1,0]
	v_pk_mul_f32 v[24:25], v[24:25], v[240:241] op_sel_hi:[1,0]
	v_pk_mul_f32 v[26:27], v[26:27], v[236:237] op_sel_hi:[1,0]
	v_pk_mul_f32 v[28:29], v[28:29], v[236:237] op_sel_hi:[1,0]
	v_pk_mul_f32 v[30:31], v[30:31], v[240:241] op_sel_hi:[1,0]
	v_pk_mul_f32 v[32:33], v[32:33], v[240:241] op_sel_hi:[1,0]
; #define SBAR() __builtin_amdgcn_sched_barrier(0)
; __device__ __forceinline__ void partialSM(f32x16& p0, f32x16& p1, float& m_reg, float& mn, float& alpha) {
;     ...
;   float mnC = -mn * C;
;   for (int r = 0; r < 16; ++r) p0[r] = fmaf(p0[r], C, mnC); for (int r = 0; r < 16; ++r) p1[r] = fmaf(p1[r], C, mnC);
;   for (int r = 0; r < 16; ++r) p0[r] = __builtin_amdgcn_exp2f(p0[r]);
; }
; __device__ __forceinline__ void finishSM(f32x16& p0, f32x16& p1, float alpha, float& l_reg, bf16x8& pa0, bf16x8& pa1, bf16x8& pa2, bf16x8& pa3) {
;   for (int r = 0; r < 16; ++r) p1[r] = __builtin_amdgcn_exp2f(p1[r]);
;   float ps = 0; for (int r = 0; r < 16; ++r) ps += p0[r]; for (int r = 0; r < 16; ++r) ps += p1[r];
;   { auto rr = __builtin_amdgcn_permlane32_swap(__float_as_uint(ps), __float_as_uint(ps), false, false);
;     ps = __uint_as_float(rr[0]) + __uint_as_float(rr[1]); }
;   l_reg = l_reg * alpha + ps;
;     ...
;   PK4(p0, 0, pa0); PK4(p0, 8, pa1); PK4(p1, 0, pa2); PK4(p1, 8, pa3);
; template <int B> __device__ __forceinline__ void pv_reads(VFrag& f, int vb) {
;   constexpr int base = (B >> 2) * 16384 + (B & 3) * 512;
;   f.l0 = tr_read<base + 0 * 4096>(vb); f.h0 = tr_read<base + 0 * 4096 + 2048>(vb); f.l1 = tr_read<base + 1 * 4096>(vb); f.h1 = tr_read<base + 1 * 4096 + 2048>(vb);
;   f.l2 = tr_read<base + 2 * 4096>(vb); f.h2 = tr_read<base + 2 * 4096 + 2048>(vb); f.l3 = tr_read<base + 3 * 4096>(vb); f.h3 = tr_read<base + 3 * 4096 + 2048>(vb);
; }
; __device__ __forceinline__ void pv_mma(f32x16& od, const VFrag& f, bf16x8 pa0, bf16x8 pa1, bf16x8 pa2, bf16x8 pa3) {
;     ...
;   od = __builtin_amdgcn_mfma_f32_32x32x16_bf16(pa0, PKV(f.l0, f.h0), od, 0, 0, 0);
;   od = __builtin_amdgcn_mfma_f32_32x32x16_bf16(pa1, PKV(f.l1, f.h1), od, 0, 0, 0);
;   od = __builtin_amdgcn_mfma_f32_32x32x16_bf16(pa2, PKV(f.l2, f.h2), od, 0, 0, 0);
;   od = __builtin_amdgcn_mfma_f32_32x32x16_bf16(pa3, PKV(f.l3, f.h3), od, 0, 0, 0);
;     ...
; }
; __device__ __forceinline__ void pv_all(f32x16* o, int vb, bf16x8 pa0, bf16x8 pa1, bf16x8 pa2, bf16x8 pa3) {
;   VFrag fc, fn;
;   pv_reads<0>(fc, vb);
;   PV_STEP(0); PV_STEP(1); PV_STEP(2); PV_STEP(3); PV_STEP(4); PV_STEP(5); PV_STEP(6);
;   asm volatile("s_waitcnt lgkmcnt(0)" ::: "memory"); SBAR(); pv_mma(o[7], fc, pa0, pa1, pa2, pa3);
; }
.Lat_x_noresc:
	v_fmamk_f32 v130, v130, 0x3e0293ee, v251
	v_fmamk_f32 v131, v131, 0x3e0293ee, v251
	v_fmamk_f32 v132, v132, 0x3e0293ee, v251
	v_fmamk_f32 v133, v133, 0x3e0293ee, v251
	v_fmamk_f32 v134, v134, 0x3e0293ee, v238
	v_fmamk_f32 v135, v135, 0x3e0293ee, v238
	v_fmamk_f32 v136, v136, 0x3e0293ee, v238
	v_fmamk_f32 v137, v137, 0x3e0293ee, v238
	v_fmamk_f32 v138, v138, 0x3e0293ee, v251
	v_fmamk_f32 v139, v139, 0x3e0293ee, v251
	v_fmamk_f32 v140, v140, 0x3e0293ee, v251
	v_fmamk_f32 v141, v141, 0x3e0293ee, v251
	v_fmamk_f32 v142, v142, 0x3e0293ee, v238
	v_fmamk_f32 v143, v143, 0x3e0293ee, v238
	v_fmamk_f32 v144, v144, 0x3e0293ee, v238
	v_fmamk_f32 v145, v145, 0x3e0293ee, v238
	v_fmamk_f32 v146, v146, 0x3e0293ee, v251
	v_fmamk_f32 v147, v147, 0x3e0293ee, v251
	v_fmamk_f32 v148, v148, 0x3e0293ee, v251
	v_fmamk_f32 v149, v149, 0x3e0293ee, v251
	v_fmamk_f32 v150, v150, 0x3e0293ee, v238
	v_fmamk_f32 v151, v151, 0x3e0293ee, v238
	v_fmamk_f32 v152, v152, 0x3e0293ee, v238
	v_fmamk_f32 v153, v153, 0x3e0293ee, v238
	v_fmamk_f32 v154, v154, 0x3e0293ee, v251
	v_fmamk_f32 v155, v155, 0x3e0293ee, v251
	v_fmamk_f32 v156, v156, 0x3e0293ee, v251
	v_fmamk_f32 v157, v157, 0x3e0293ee, v251
	v_fmamk_f32 v158, v158, 0x3e0293ee, v238
	v_fmamk_f32 v159, v159, 0x3e0293ee, v238
	v_fmamk_f32 v160, v160, 0x3e0293ee, v238
	v_fmamk_f32 v161, v161, 0x3e0293ee, v238
	v_exp_f32_e32 v130, v130
	v_exp_f32_e32 v131, v131
	v_exp_f32_e32 v132, v132
	v_exp_f32_e32 v133, v133
	v_exp_f32_e32 v134, v134
	v_exp_f32_e32 v135, v135
	v_exp_f32_e32 v136, v136
	v_exp_f32_e32 v137, v137
	v_exp_f32_e32 v138, v138
	v_exp_f32_e32 v139, v139
	v_exp_f32_e32 v140, v140
	v_exp_f32_e32 v141, v141
	v_exp_f32_e32 v142, v142
	v_exp_f32_e32 v143, v143
	v_exp_f32_e32 v144, v144
	v_exp_f32_e32 v145, v145
	v_exp_f32_e32 v146, v146
	v_exp_f32_e32 v147, v147
	v_exp_f32_e32 v148, v148
	v_exp_f32_e32 v149, v149
	v_exp_f32_e32 v150, v150
	v_exp_f32_e32 v151, v151
	v_exp_f32_e32 v152, v152
	v_exp_f32_e32 v153, v153
	v_exp_f32_e32 v154, v154
	v_exp_f32_e32 v155, v155
	v_exp_f32_e32 v156, v156
	v_exp_f32_e32 v157, v157
	v_exp_f32_e32 v158, v158
	v_exp_f32_e32 v159, v159
	v_exp_f32_e32 v160, v160
	v_exp_f32_e32 v161, v161
	v_add_f32_e32 v194, v130, v131
	v_add_f32_e32 v194, v194, v132
	v_add_f32_e32 v194, v194, v133
	v_add_f32_e32 v194, v194, v138
	v_add_f32_e32 v194, v194, v139
	v_add_f32_e32 v194, v194, v140
	v_add_f32_e32 v194, v194, v141
	v_add_f32_e32 v194, v194, v146
	v_add_f32_e32 v194, v194, v147
	v_add_f32_e32 v194, v194, v148
	v_add_f32_e32 v194, v194, v149
	v_add_f32_e32 v194, v194, v154
	v_add_f32_e32 v194, v194, v155
	v_add_f32_e32 v194, v194, v156
	v_add_f32_e32 v194, v194, v157
	v_add_f32_e32 v195, v134, v135
	v_add_f32_e32 v195, v195, v136
	v_add_f32_e32 v195, v195, v137
	v_add_f32_e32 v195, v195, v142
	v_add_f32_e32 v195, v195, v143
	v_add_f32_e32 v195, v195, v144
	v_add_f32_e32 v195, v195, v145
	v_add_f32_e32 v195, v195, v150
	v_add_f32_e32 v195, v195, v151
	v_add_f32_e32 v195, v195, v152
	v_add_f32_e32 v195, v195, v153
	v_add_f32_e32 v195, v195, v158
	v_add_f32_e32 v195, v195, v159
	v_add_f32_e32 v195, v195, v160
	v_add_f32_e32 v195, v195, v161
	v_add_f32_e32 v250, v250, v194
	v_add_f32_e32 v234, v234, v195
	v_cvt_pk_bf16_f32 v130, v130, v131
	v_cvt_pk_bf16_f32 v131, v132, v133
	v_cvt_pk_bf16_f32 v132, v138, v139
	v_cvt_pk_bf16_f32 v133, v140, v141
	v_cvt_pk_bf16_f32 v134, v134, v135
	v_cvt_pk_bf16_f32 v135, v136, v137
	v_cvt_pk_bf16_f32 v136, v142, v143
	v_cvt_pk_bf16_f32 v137, v144, v145
	v_cvt_pk_bf16_f32 v138, v146, v147
	v_cvt_pk_bf16_f32 v139, v148, v149
	v_cvt_pk_bf16_f32 v140, v154, v155
	v_cvt_pk_bf16_f32 v141, v156, v157
	v_cvt_pk_bf16_f32 v142, v150, v151
	v_cvt_pk_bf16_f32 v143, v152, v153
	v_cvt_pk_bf16_f32 v144, v158, v159
	v_cvt_pk_bf16_f32 v145, v160, v161
	v_add_u32_e32 v244, s98, v248
	ds_read_b64_tr_b16 v[146:147], v244
	ds_read_b64_tr_b16 v[148:149], v244 offset:4096
	ds_read_b64_tr_b16 v[150:151], v244 offset:8192
	ds_read_b64_tr_b16 v[152:153], v244 offset:12288
	ds_read_b64_tr_b16 v[154:155], v244 offset:256
	ds_read_b64_tr_b16 v[156:157], v244 offset:4352
	ds_read_b64_tr_b16 v[158:159], v244 offset:8448
	ds_read_b64_tr_b16 v[160:161], v244 offset:12544
	ds_read_b64_tr_b16 v[194:195], v244 offset:512
	ds_read_b64_tr_b16 v[196:197], v244 offset:4608
	ds_read_b64_tr_b16 v[198:199], v244 offset:8704
	ds_read_b64_tr_b16 v[200:201], v244 offset:12800
	s_waitcnt lgkmcnt(8)
	v_mfma_f32_16x16x32_bf16 v[2:5], v[146:149], v[130:133], v[2:5]
	v_mfma_f32_16x16x32_bf16 v[6:9], v[146:149], v[134:137], v[6:9]
	v_mfma_f32_16x16x32_bf16 v[2:5], v[150:153], v[138:141], v[2:5]
	v_mfma_f32_16x16x32_bf16 v[6:9], v[150:153], v[142:145], v[6:9]
	ds_read_b64_tr_b16 v[146:147], v244 offset:768
	ds_read_b64_tr_b16 v[148:149], v244 offset:4864
	ds_read_b64_tr_b16 v[150:151], v244 offset:8960
	ds_read_b64_tr_b16 v[152:153], v244 offset:13056
	s_waitcnt lgkmcnt(8)
	v_mfma_f32_16x16x32_bf16 v[10:13], v[154:157], v[130:133], v[10:13]
	v_mfma_f32_16x16x32_bf16 v[14:17], v[154:157], v[134:137], v[14:17]
	v_mfma_f32_16x16x32_bf16 v[10:13], v[158:161], v[138:141], v[10:13]
	v_mfma_f32_16x16x32_bf16 v[14:17], v[158:161], v[142:145], v[14:17]
	ds_read_b64_tr_b16 v[154:155], v244 offset:1024
	ds_read_b64_tr_b16 v[156:157], v244 offset:5120
	ds_read_b64_tr_b16 v[158:159], v244 offset:9216
	ds_read_b64_tr_b16 v[160:161], v244 offset:13312
	s_waitcnt lgkmcnt(8)
; #define SBAR() __builtin_amdgcn_sched_barrier(0)
; #define PV_STEP(B) do { pv_reads<(B) + 1>(fn, vb); asm volatile("s_waitcnt lgkmcnt(8)" ::: "memory"); SBAR(); pv_mma(o[B], fc, pa0, pa1, pa2, pa3); SBAR(); fc = fn; } while (0)
; template <int B> __device__ __forceinline__ void pv_reads(VFrag& f, int vb) {
;   constexpr int base = (B >> 2) * 16384 + (B & 3) * 512;
;   f.l0 = tr_read<base + 0 * 4096>(vb); f.h0 = tr_read<base + 0 * 4096 + 2048>(vb); f.l1 = tr_read<base + 1 * 4096>(vb); f.h1 = tr_read<base + 1 * 4096 + 2048>(vb);
;   f.l2 = tr_read<base + 2 * 4096>(vb); f.h2 = tr_read<base + 2 * 4096 + 2048>(vb); f.l3 = tr_read<base + 3 * 4096>(vb); f.h3 = tr_read<base + 3 * 4096 + 2048>(vb);
; }
; __device__ __forceinline__ void pv_mma(f32x16& od, const VFrag& f, bf16x8 pa0, bf16x8 pa1, bf16x8 pa2, bf16x8 pa3) {
;     ...
;   od = __builtin_amdgcn_mfma_f32_32x32x16_bf16(pa0, PKV(f.l0, f.h0), od, 0, 0, 0);
;   od = __builtin_amdgcn_mfma_f32_32x32x16_bf16(pa1, PKV(f.l1, f.h1), od, 0, 0, 0);
;   od = __builtin_amdgcn_mfma_f32_32x32x16_bf16(pa2, PKV(f.l2, f.h2), od, 0, 0, 0);
;   od = __builtin_amdgcn_mfma_f32_32x32x16_bf16(pa3, PKV(f.l3, f.h3), od, 0, 0, 0);
;     ...
; }
; __device__ __forceinline__ void pv_all(f32x16* o, int vb, bf16x8 pa0, bf16x8 pa1, bf16x8 pa2, bf16x8 pa3) {
;   VFrag fc, fn;
;   pv_reads<0>(fc, vb);
;   PV_STEP(0); PV_STEP(1); PV_STEP(2); PV_STEP(3); PV_STEP(4); PV_STEP(5); PV_STEP(6);
;   asm volatile("s_waitcnt lgkmcnt(0)" ::: "memory"); SBAR(); pv_mma(o[7], fc, pa0, pa1, pa2, pa3);
; }
	v_mfma_f32_16x16x32_bf16 v[114:117], v[194:197], v[130:133], v[114:117]
	v_mfma_f32_16x16x32_bf16 v[118:121], v[194:197], v[134:137], v[118:121]
	v_mfma_f32_16x16x32_bf16 v[114:117], v[198:201], v[138:141], v[114:117]
	v_mfma_f32_16x16x32_bf16 v[118:121], v[198:201], v[142:145], v[118:121]
	ds_read_b64_tr_b16 v[194:195], v244 offset:1280
	ds_read_b64_tr_b16 v[196:197], v244 offset:5376
	ds_read_b64_tr_b16 v[198:199], v244 offset:9472
	ds_read_b64_tr_b16 v[200:201], v244 offset:13568
	s_waitcnt lgkmcnt(8)
	v_mfma_f32_16x16x32_bf16 v[122:125], v[146:149], v[130:133], v[122:125]
	v_mfma_f32_16x16x32_bf16 v[126:129], v[146:149], v[134:137], v[126:129]
	v_mfma_f32_16x16x32_bf16 v[122:125], v[150:153], v[138:141], v[122:125]
	v_mfma_f32_16x16x32_bf16 v[126:129], v[150:153], v[142:145], v[126:129]
	ds_read_b64_tr_b16 v[146:147], v244 offset:1536
	ds_read_b64_tr_b16 v[148:149], v244 offset:5632
	ds_read_b64_tr_b16 v[150:151], v244 offset:9728
	ds_read_b64_tr_b16 v[152:153], v244 offset:13824
	s_waitcnt lgkmcnt(8)
	v_mfma_f32_16x16x32_bf16 v[98:101], v[154:157], v[130:133], v[98:101]
	v_mfma_f32_16x16x32_bf16 v[102:105], v[154:157], v[134:137], v[102:105]
	v_mfma_f32_16x16x32_bf16 v[98:101], v[158:161], v[138:141], v[98:101]
	v_mfma_f32_16x16x32_bf16 v[102:105], v[158:161], v[142:145], v[102:105]
	ds_read_b64_tr_b16 v[154:155], v244 offset:1792
	ds_read_b64_tr_b16 v[156:157], v244 offset:5888
	ds_read_b64_tr_b16 v[158:159], v244 offset:9984
	ds_read_b64_tr_b16 v[160:161], v244 offset:14080
	s_waitcnt lgkmcnt(8)
	v_mfma_f32_16x16x32_bf16 v[106:109], v[194:197], v[130:133], v[106:109]
	v_mfma_f32_16x16x32_bf16 v[110:113], v[194:197], v[134:137], v[110:113]
	v_mfma_f32_16x16x32_bf16 v[106:109], v[198:201], v[138:141], v[106:109]
	v_mfma_f32_16x16x32_bf16 v[110:113], v[198:201], v[142:145], v[110:113]
	ds_read_b64_tr_b16 v[194:195], v244 offset:16384
	ds_read_b64_tr_b16 v[196:197], v244 offset:20480
	ds_read_b64_tr_b16 v[198:199], v244 offset:24576
	ds_read_b64_tr_b16 v[200:201], v244 offset:28672
	s_waitcnt lgkmcnt(8)
	v_mfma_f32_16x16x32_bf16 v[82:85], v[146:149], v[130:133], v[82:85]
	v_mfma_f32_16x16x32_bf16 v[86:89], v[146:149], v[134:137], v[86:89]
	v_mfma_f32_16x16x32_bf16 v[82:85], v[150:153], v[138:141], v[82:85]
	v_mfma_f32_16x16x32_bf16 v[86:89], v[150:153], v[142:145], v[86:89]
	ds_read_b64_tr_b16 v[146:147], v244 offset:16640
	ds_read_b64_tr_b16 v[148:149], v244 offset:20736
	ds_read_b64_tr_b16 v[150:151], v244 offset:24832
	ds_read_b64_tr_b16 v[152:153], v244 offset:28928
	s_waitcnt lgkmcnt(8)
	v_mfma_f32_16x16x32_bf16 v[90:93], v[154:157], v[130:133], v[90:93]
	v_mfma_f32_16x16x32_bf16 v[94:97], v[154:157], v[134:137], v[94:97]
	v_mfma_f32_16x16x32_bf16 v[90:93], v[158:161], v[138:141], v[90:93]
	v_mfma_f32_16x16x32_bf16 v[94:97], v[158:161], v[142:145], v[94:97]
	ds_read_b64_tr_b16 v[154:155], v244 offset:16896
	ds_read_b64_tr_b16 v[156:157], v244 offset:20992
	ds_read_b64_tr_b16 v[158:159], v244 offset:25088
	ds_read_b64_tr_b16 v[160:161], v244 offset:29184
	s_waitcnt lgkmcnt(8)
	v_mfma_f32_16x16x32_bf16 v[66:69], v[194:197], v[130:133], v[66:69]
	v_mfma_f32_16x16x32_bf16 v[70:73], v[194:197], v[134:137], v[70:73]
	v_mfma_f32_16x16x32_bf16 v[66:69], v[198:201], v[138:141], v[66:69]
	v_mfma_f32_16x16x32_bf16 v[70:73], v[198:201], v[142:145], v[70:73]
	ds_read_b64_tr_b16 v[194:195], v244 offset:17152
	ds_read_b64_tr_b16 v[196:197], v244 offset:21248
	ds_read_b64_tr_b16 v[198:199], v244 offset:25344
	ds_read_b64_tr_b16 v[200:201], v244 offset:29440
	s_waitcnt lgkmcnt(8)
	v_mfma_f32_16x16x32_bf16 v[74:77], v[146:149], v[130:133], v[74:77]
	v_mfma_f32_16x16x32_bf16 v[78:81], v[146:149], v[134:137], v[78:81]
	v_mfma_f32_16x16x32_bf16 v[74:77], v[150:153], v[138:141], v[74:77]
	v_mfma_f32_16x16x32_bf16 v[78:81], v[150:153], v[142:145], v[78:81]
	ds_read_b64_tr_b16 v[146:147], v244 offset:17408
	ds_read_b64_tr_b16 v[148:149], v244 offset:21504
	ds_read_b64_tr_b16 v[150:151], v244 offset:25600
	ds_read_b64_tr_b16 v[152:153], v244 offset:29696
	s_waitcnt lgkmcnt(8)
	v_mfma_f32_16x16x32_bf16 v[50:53], v[154:157], v[130:133], v[50:53]
	v_mfma_f32_16x16x32_bf16 v[54:57], v[154:157], v[134:137], v[54:57]
	v_mfma_f32_16x16x32_bf16 v[50:53], v[158:161], v[138:141], v[50:53]
	v_mfma_f32_16x16x32_bf16 v[54:57], v[158:161], v[142:145], v[54:57]
	ds_read_b64_tr_b16 v[154:155], v244 offset:17664
	ds_read_b64_tr_b16 v[156:157], v244 offset:21760
	ds_read_b64_tr_b16 v[158:159], v244 offset:25856
	ds_read_b64_tr_b16 v[160:161], v244 offset:29952
	s_waitcnt lgkmcnt(8)
	v_mfma_f32_16x16x32_bf16 v[58:61], v[194:197], v[130:133], v[58:61]
	v_mfma_f32_16x16x32_bf16 v[62:65], v[194:197], v[134:137], v[62:65]
	v_mfma_f32_16x16x32_bf16 v[58:61], v[198:201], v[138:141], v[58:61]
	v_mfma_f32_16x16x32_bf16 v[62:65], v[198:201], v[142:145], v[62:65]
	ds_read_b64_tr_b16 v[194:195], v244 offset:17920
	ds_read_b64_tr_b16 v[196:197], v244 offset:22016
	ds_read_b64_tr_b16 v[198:199], v244 offset:26112
	ds_read_b64_tr_b16 v[200:201], v244 offset:30208
	s_waitcnt lgkmcnt(8)
	v_mfma_f32_16x16x32_bf16 v[34:37], v[146:149], v[130:133], v[34:37]
	v_mfma_f32_16x16x32_bf16 v[38:41], v[146:149], v[134:137], v[38:41]
	v_mfma_f32_16x16x32_bf16 v[34:37], v[150:153], v[138:141], v[34:37]
	v_mfma_f32_16x16x32_bf16 v[38:41], v[150:153], v[142:145], v[38:41]
	ds_read_b64_tr_b16 v[146:147], v244 offset:18176
	ds_read_b64_tr_b16 v[148:149], v244 offset:22272
	ds_read_b64_tr_b16 v[150:151], v244 offset:26368
	ds_read_b64_tr_b16 v[152:153], v244 offset:30464
	s_waitcnt lgkmcnt(8)
	v_mfma_f32_16x16x32_bf16 v[42:45], v[154:157], v[130:133], v[42:45]
	v_mfma_f32_16x16x32_bf16 v[46:49], v[154:157], v[134:137], v[46:49]
	v_mfma_f32_16x16x32_bf16 v[42:45], v[158:161], v[138:141], v[42:45]
	v_mfma_f32_16x16x32_bf16 v[46:49], v[158:161], v[142:145], v[46:49]
	s_waitcnt lgkmcnt(4)
	v_mfma_f32_16x16x32_bf16 v[18:21], v[194:197], v[130:133], v[18:21]
	v_mfma_f32_16x16x32_bf16 v[22:25], v[194:197], v[134:137], v[22:25]
	v_mfma_f32_16x16x32_bf16 v[18:21], v[198:201], v[138:141], v[18:21]
	v_mfma_f32_16x16x32_bf16 v[22:25], v[198:201], v[142:145], v[22:25]
	s_waitcnt lgkmcnt(0)
	v_mfma_f32_16x16x32_bf16 v[26:29], v[146:149], v[130:133], v[26:29]
	v_mfma_f32_16x16x32_bf16 v[30:33], v[146:149], v[134:137], v[30:33]
	v_mfma_f32_16x16x32_bf16 v[26:29], v[150:153], v[138:141], v[26:29]
	v_mfma_f32_16x16x32_bf16 v[30:33], v[150:153], v[142:145], v[30:33]
	s_waitcnt vmcnt(0)
	s_barrier
; #define SBAR() __builtin_amdgcn_sched_barrier(0)
; __device__ __forceinline__ int crow(int r, int hi) { return (r & 3) + 8 * (r >> 2) + 4 * hi; }
; __device__ __forceinline__ int v_rd_base(int lane) { return ((lane & 3) << 3) | (((lane >> 2) & 3) << 6) | (((lane >> 4) & 1) << 5) | (((lane >> 5) & 1) << 8); }
; __device__ __forceinline__ int crow(int r, int hi) { return (r & 3) + 8 * (r >> 2) + 4 * hi; }
; __device__ __forceinline__ void attn_body256(const bf16_t* __restrict__ Qb, const bf16_t* __restrict__ Kh, const bf16_t* __restrict__ Vh,
;                                              bf16_t* Ob, int seq, unsigned char* lds, float lam, int MODE, bf16_t* Ab, const float* wsub) {
;     ...
;   const int NT = seq / KVBLK;
;   A2_DMA(0, 0); A2_DMA(1, 1);
;   float m_reg = -1e30f, l_reg = 0; f32x16 o[8] = {}; bf16x8 qr[8];
;   const bf16_t* Qw = Qb + (long)(wid * QBLK + r32) * LDQ + hi * 8;
; #pragma unroll
;   for (int d0 = 0; d0 < 8; ++d0) qr[d0] = *reinterpret_cast<const bf16x8*>(Qw + d0 * 16);
;   const int vb0 = (int)(uintptr_t)lds + v_rd_base(lane);
;   asm volatile("s_waitcnt vmcnt(0)" ::: "memory"); __syncthreads();
;   for (int j = 0; j < NT; ++j) {
;     const int b = j & 1;
;     f32x16 p0, p1; float mn, alpha; bf16x8 pa0, pa1, pa2, pa3;
;     SBAR(); qkt(p0, p1, (const bf16_t*)(lds + A2_KOFF + b * A2_KBUF), qr, r32, hi);
;     partialSM(p0, p1, m_reg, mn, alpha);
;     if (__any(alpha < 1.f)) { if (hi == 0) al_l[r32] = alpha; asm volatile("s_waitcnt lgkmcnt(0)" ::: "memory");
; #pragma unroll
;       for (int r = 0; r < 16; ++r) { const float a = al_l[crow(r, hi)];
; #pragma unroll
;         for (int d = 0; d < 8; ++d) o[d][r] *= a; } }
;     finishSM(p0, p1, alpha, l_reg, pa0, pa1, pa2, pa3); SBAR();
;     pv_all(o, vb0 + b * A2_VBUF, pa0, pa1, pa2, pa3);
;     asm volatile("s_waitcnt vmcnt(0)" ::: "memory"); __syncthreads();
;     if (j + 2 < NT) A2_DMA(j + 2, b);
	s_xor_b32 s9, s25, 1
	s_lshl_b32 s9, s9, 14
	s_add_i32 s9, s9, 0x10000
	v_add_u32_e32 v230, s9, v232
	v_add_u32_e32 v247, s9, v233
	v_add_u32_e32 v239, s9, v242
	v_add_u32_e32 v245, s9, v243
	ds_read_b128 v[194:197], v230
	ds_read_b128 v[198:201], v230 offset:4096
	ds_read_b128 v[202:205], v230 offset:8192
	ds_read_b128 v[206:209], v230 offset:12288
	ds_read_b128 v[210:213], v247
	ds_read_b128 v[214:217], v247 offset:4096
	s_cmp_ge_u32 s13, s19
	s_cbranch_scc1 .Lat_x_nodma
	v_lshl_add_u64 v[130:131], v[220:221], 0, s[14:15]
	v_lshl_add_u64 v[132:133], v[222:223], 0, s[14:15]
	v_lshl_add_u64 v[134:135], v[224:225], 0, s[14:15]
	v_lshl_add_u64 v[136:137], v[226:227], 0, s[14:15]
	v_lshl_add_u64 v[138:139], v[134:135], 0, s[54:55]
	v_lshl_add_u64 v[134:135], v[134:135], 0, s[4:5]
	v_lshl_add_u64 v[140:141], v[136:137], 0, s[54:55]
	v_lshl_add_u64 v[136:137], v[136:137], 0, s[4:5]
	s_add_i32 s9, s22, s24
	s_add_i32 s8, s21, s100
	s_mov_b32 m0, s9
	s_nop 0
	global_load_lds_dwordx4 v[130:131], off
	s_add_i32 m0, s9, 0x2000
	s_nop 0
	global_load_lds_dwordx4 v[132:133], off
	s_mov_b32 m0, s8
	s_nop 0
	global_load_lds_dwordx4 v[138:139], off
	s_add_i32 m0, s8, 0x4000
	s_nop 0
	global_load_lds_dwordx4 v[134:135], off
	s_add_i32 m0, s8, 0x2000
	s_nop 0
	global_load_lds_dwordx4 v[140:141], off
	s_add_i32 m0, s8, 0x6000
	s_nop 0
	global_load_lds_dwordx4 v[136:137], off

; __device__ __forceinline__ void partialSM(f32x16& p0, f32x16& p1, float& m_reg, float& mn, float& alpha) {
;   constexpr float C = SCALE * 1.4426950408889634f;
;   float pmax = p0[0]; for (int r = 1; r < 16; ++r) pmax = fmaxf(pmax, p0[r]); for (int r = 0; r < 16; ++r) pmax = fmaxf(pmax, p1[r]);
;   { auto rr = __builtin_amdgcn_permlane32_swap(__float_as_uint(pmax), __float_as_uint(pmax), false, false);
;     pmax = fmaxf(__uint_as_float(rr[0]), __uint_as_float(rr[1])); }
;   if (__builtin_expect(__all(pmax - m_reg <= THR / SCALE), 1)) { mn = m_reg; alpha = 1.f; }
;   else { mn = fmaxf(m_reg, pmax); alpha = __builtin_amdgcn_exp2f((m_reg - mn) * C); m_reg = mn; }
; __device__ __forceinline__ void qkt(f32x16& p0, f32x16& p1, const bf16_t* Ks, const bf16x8* qr, int r32, int hi) {
;   p0 = f32x16{}; p1 = f32x16{};
;   for (int d0 = 0; d0 < 8; ++d0) { int cb = (d0 * 16 + hi * 8) * 2;
;     bf16x8 b0 = *reinterpret_cast<const bf16x8*>((const char*)Ks + KSWZ(r32, cb));
;     bf16x8 b1 = *reinterpret_cast<const bf16x8*>((const char*)Ks + KSWZ(32 + r32, cb));
;     p0 = __builtin_amdgcn_mfma_f32_32x32x16_bf16(b0, qr[d0], p0, 0, 0, 0);
;     p1 = __builtin_amdgcn_mfma_f32_32x32x16_bf16(b1, qr[d0], p1, 0, 0, 0); }
.Lat_y_nodma:
.Lat_y_qk:
	s_add_i32 s8, s13, -2
	s_and_b32 s25, s8, 1
	s_lshl_b32 s24, s25, 14
	s_add_i32 s8, s24, 0x10000
	v_add_u32_e32 v230, s8, v232
	v_add_u32_e32 v247, s8, v233
	v_add_u32_e32 v239, s8, v242
	v_add_u32_e32 v245, s8, v243
	s_setprio 1
	ds_read_b128 v[194:197], v230
	ds_read_b128 v[198:201], v230 offset:4096
	ds_read_b128 v[202:205], v230 offset:8192
	ds_read_b128 v[206:209], v230 offset:12288
	ds_read_b128 v[210:213], v247
	ds_read_b128 v[214:217], v247 offset:4096
	s_waitcnt lgkmcnt(5)
	v_mfma_f32_16x16x32_bf16 v[130:133], v[194:197], v[162:165], 0
	v_mfma_f32_16x16x32_bf16 v[134:137], v[194:197], v[178:181], 0
	ds_read_b128 v[194:197], v247 offset:8192
	s_waitcnt lgkmcnt(5)
	v_mfma_f32_16x16x32_bf16 v[138:141], v[198:201], v[162:165], 0
	v_mfma_f32_16x16x32_bf16 v[142:145], v[198:201], v[178:181], 0
	ds_read_b128 v[198:201], v247 offset:12288
	s_waitcnt lgkmcnt(5)
	v_mfma_f32_16x16x32_bf16 v[146:149], v[202:205], v[162:165], 0
	v_mfma_f32_16x16x32_bf16 v[150:153], v[202:205], v[178:181], 0
	ds_read_b128 v[202:205], v239
	s_waitcnt lgkmcnt(5)
	v_mfma_f32_16x16x32_bf16 v[154:157], v[206:209], v[162:165], 0
	v_mfma_f32_16x16x32_bf16 v[158:161], v[206:209], v[178:181], 0
	ds_read_b128 v[206:209], v239 offset:4096
	s_waitcnt lgkmcnt(5)
	v_mfma_f32_16x16x32_bf16 v[130:133], v[210:213], v[166:169], v[130:133]
	v_mfma_f32_16x16x32_bf16 v[134:137], v[210:213], v[182:185], v[134:137]
	ds_read_b128 v[210:213], v239 offset:8192
	s_waitcnt lgkmcnt(5)
	v_mfma_f32_16x16x32_bf16 v[138:141], v[214:217], v[166:169], v[138:141]
	v_mfma_f32_16x16x32_bf16 v[142:145], v[214:217], v[182:185], v[142:145]
	ds_read_b128 v[214:217], v239 offset:12288
	s_waitcnt lgkmcnt(5)
	v_mfma_f32_16x16x32_bf16 v[146:149], v[194:197], v[166:169], v[146:149]
	v_mfma_f32_16x16x32_bf16 v[150:153], v[194:197], v[182:185], v[150:153]
	ds_read_b128 v[194:197], v245
	s_waitcnt lgkmcnt(5)
	v_mfma_f32_16x16x32_bf16 v[154:157], v[198:201], v[166:169], v[154:157]
	v_mfma_f32_16x16x32_bf16 v[158:161], v[198:201], v[182:185], v[158:161]
	ds_read_b128 v[198:201], v245 offset:4096
	s_waitcnt lgkmcnt(5)
	v_mfma_f32_16x16x32_bf16 v[130:133], v[202:205], v[170:173], v[130:133]
	v_mfma_f32_16x16x32_bf16 v[134:137], v[202:205], v[186:189], v[134:137]
	ds_read_b128 v[202:205], v245 offset:8192
	s_waitcnt lgkmcnt(5)
	v_mfma_f32_16x16x32_bf16 v[138:141], v[206:209], v[170:173], v[138:141]
	v_mfma_f32_16x16x32_bf16 v[142:145], v[206:209], v[186:189], v[142:145]
	ds_read_b128 v[206:209], v245 offset:12288
	s_waitcnt lgkmcnt(5)
	v_mfma_f32_16x16x32_bf16 v[146:149], v[210:213], v[170:173], v[146:149]
	v_mfma_f32_16x16x32_bf16 v[150:153], v[210:213], v[186:189], v[150:153]
	s_waitcnt lgkmcnt(4)
	v_mfma_f32_16x16x32_bf16 v[154:157], v[214:217], v[170:173], v[154:157]
	v_mfma_f32_16x16x32_bf16 v[158:161], v[214:217], v[186:189], v[158:161]
	s_waitcnt lgkmcnt(3)
	v_mfma_f32_16x16x32_bf16 v[130:133], v[194:197], v[174:177], v[130:133]
	v_mfma_f32_16x16x32_bf16 v[134:137], v[194:197], v[190:193], v[134:137]
	s_waitcnt lgkmcnt(2)
	v_mfma_f32_16x16x32_bf16 v[138:141], v[198:201], v[174:177], v[138:141]
	v_mfma_f32_16x16x32_bf16 v[142:145], v[198:201], v[190:193], v[142:145]
	s_waitcnt lgkmcnt(1)
	v_mfma_f32_16x16x32_bf16 v[146:149], v[202:205], v[174:177], v[146:149]
	v_mfma_f32_16x16x32_bf16 v[150:153], v[202:205], v[190:193], v[150:153]
	s_waitcnt lgkmcnt(0)
	v_mfma_f32_16x16x32_bf16 v[154:157], v[206:209], v[174:177], v[154:157]
	v_mfma_f32_16x16x32_bf16 v[158:161], v[206:209], v[190:193], v[158:161]
	s_setprio 0
	s_nop 6
	v_max3_f32 v194, v130, v131, v132
	v_max3_f32 v194, v194, v133, v138
	v_max3_f32 v194, v194, v139, v140
	v_max3_f32 v194, v194, v141, v146
	v_max3_f32 v194, v194, v147, v148
	v_max3_f32 v194, v194, v149, v154
	v_max3_f32 v194, v194, v155, v156
	v_max_f32_e32 v194, v194, v157
	v_max3_f32 v195, v134, v135, v136
	v_max3_f32 v195, v195, v137, v142
	v_max3_f32 v195, v195, v143, v144
	v_max3_f32 v195, v195, v145, v150
	v_max3_f32 v195, v195, v151, v152
	v_max3_f32 v195, v195, v153, v158
	v_max3_f32 v195, v195, v159, v160
	v_max_f32_e32 v195, v195, v161
	v_mov_b32_e32 v196, v194
	v_mov_b32_e32 v197, v195
	s_nop 1
	v_permlane32_swap_b32_e32 v194, v196
	v_permlane32_swap_b32_e32 v195, v197
	v_max_f32_e32 v194, v194, v196
	v_max_f32_e32 v195, v195, v197
	v_mov_b32_e32 v196, v194
	v_mov_b32_e32 v197, v195
	s_nop 1
	v_permlane16_swap_b32_e32 v194, v196
	v_permlane16_swap_b32_e32 v195, v197
	v_max_f32_e32 v194, v194, v196
	v_max_f32_e32 v195, v195, v197
	v_sub_f32_e32 v196, v194, v249
	v_sub_f32_e32 v197, v195, v246
	v_max_f32_e32 v196, v196, v197
	v_cmp_nge_f32_e32 vcc, 0x42b504f3, v196
	s_cbranch_vccz .Lat_y_noresc
; __device__ __forceinline__ int crow(int r, int hi) { return (r & 3) + 8 * (r >> 2) + 4 * hi; }
; __device__ __forceinline__ int crow(int r, int hi) { return (r & 3) + 8 * (r >> 2) + 4 * hi; }
; __device__ __forceinline__ void partialSM(f32x16& p0, f32x16& p1, float& m_reg, float& mn, float& alpha) {
;     ...
;   if (__builtin_expect(__all(pmax - m_reg <= THR / SCALE), 1)) { mn = m_reg; alpha = 1.f; }
;   else { mn = fmaxf(m_reg, pmax); alpha = __builtin_amdgcn_exp2f((m_reg - mn) * C); m_reg = mn; }
; __device__ __forceinline__ void attn_body256(const bf16_t* __restrict__ Qb, const bf16_t* __restrict__ Kh, const bf16_t* __restrict__ Vh,
;                                              bf16_t* Ob, int seq, unsigned char* lds, float lam, int MODE, bf16_t* Ab, const float* wsub) {
;     ...
;     if (__any(alpha < 1.f)) { if (hi == 0) al_l[r32] = alpha; asm volatile("s_waitcnt lgkmcnt(0)" ::: "memory");
; #pragma unroll
;       for (int r = 0; r < 16; ++r) { const float a = al_l[crow(r, hi)];
; #pragma unroll
;         for (int d = 0; d < 8; ++d) o[d][r] *= a; } }
	v_max_f32_e32 v198, v249, v194
	v_max_f32_e32 v199, v246, v195
	v_sub_f32_e32 v196, v249, v198
	v_sub_f32_e32 v197, v246, v199
	v_mul_f32_e32 v196, 0x3e0293ee, v196
	v_mul_f32_e32 v197, 0x3e0293ee, v197
	v_exp_f32_e32 v236, v196
	v_exp_f32_e32 v240, v197
	v_mov_b32_e32 v249, v198
	v_mov_b32_e32 v246, v199
	v_mul_f32_e32 v251, 0xbe0293ee, v198
	v_mul_f32_e32 v238, 0xbe0293ee, v199
	v_mul_f32_e32 v250, v250, v236
	v_mul_f32_e32 v234, v234, v240
	v_pk_mul_f32 v[2:3], v[2:3], v[236:237] op_sel_hi:[1,0]
	v_pk_mul_f32 v[4:5], v[4:5], v[236:237] op_sel_hi:[1,0]
	v_pk_mul_f32 v[6:7], v[6:7], v[240:241] op_sel_hi:[1,0]
	v_pk_mul_f32 v[8:9], v[8:9], v[240:241] op_sel_hi:[1,0]
	v_pk_mul_f32 v[10:11], v[10:11], v[236:237] op_sel_hi:[1,0]
	v_pk_mul_f32 v[12:13], v[12:13], v[236:237] op_sel_hi:[1,0]
	v_pk_mul_f32 v[14:15], v[14:15], v[240:241] op_sel_hi:[1,0]
	v_pk_mul_f32 v[16:17], v[16:17], v[240:241] op_sel_hi:[1,0]
	v_pk_mul_f32 v[114:115], v[114:115], v[236:237] op_sel_hi:[1,0]
	v_pk_mul_f32 v[116:117], v[116:117], v[236:237] op_sel_hi:[1,0]
	v_pk_mul_f32 v[118:119], v[118:119], v[240:241] op_sel_hi:[1,0]
	v_pk_mul_f32 v[120:121], v[120:121], v[240:241] op_sel_hi:[1,0]
	v_pk_mul_f32 v[122:123], v[122:123], v[236:237] op_sel_hi:[1,0]
	v_pk_mul_f32 v[124:125], v[124:125], v[236:237] op_sel_hi:[1,0]
	v_pk_mul_f32 v[126:127], v[126:127], v[240:241] op_sel_hi:[1,0]
	v_pk_mul_f32 v[128:129], v[128:129], v[240:241] op_sel_hi:[1,0]
	v_pk_mul_f32 v[98:99], v[98:99], v[236:237] op_sel_hi:[1,0]
	v_pk_mul_f32 v[100:101], v[100:101], v[236:237] op_sel_hi:[1,0]
	v_pk_mul_f32 v[102:103], v[102:103], v[240:241] op_sel_hi:[1,0]
	v_pk_mul_f32 v[104:105], v[104:105], v[240:241] op_sel_hi:[1,0]
	v_pk_mul_f32 v[106:107], v[106:107], v[236:237] op_sel_hi:[1,0]
	v_pk_mul_f32 v[108:109], v[108:109], v[236:237] op_sel_hi:[1,0]
	v_pk_mul_f32 v[110:111], v[110:111], v[240:241] op_sel_hi:[1,0]
	v_pk_mul_f32 v[112:113], v[112:113], v[240:241] op_sel_hi:[1,0]
	v_pk_mul_f32 v[82:83], v[82:83], v[236:237] op_sel_hi:[1,0]
	v_pk_mul_f32 v[84:85], v[84:85], v[236:237] op_sel_hi:[1,0]
	v_pk_mul_f32 v[86:87], v[86:87], v[240:241] op_sel_hi:[1,0]
	v_pk_mul_f32 v[88:89], v[88:89], v[240:241] op_sel_hi:[1,0]
	v_pk_mul_f32 v[90:91], v[90:91], v[236:237] op_sel_hi:[1,0]
	v_pk_mul_f32 v[92:93], v[92:93], v[236:237] op_sel_hi:[1,0]
	v_pk_mul_f32 v[94:95], v[94:95], v[240:241] op_sel_hi:[1,0]
	v_pk_mul_f32 v[96:97], v[96:97], v[240:241] op_sel_hi:[1,0]
	v_pk_mul_f32 v[66:67], v[66:67], v[236:237] op_sel_hi:[1,0]
	v_pk_mul_f32 v[68:69], v[68:69], v[236:237] op_sel_hi:[1,0]
	v_pk_mul_f32 v[70:71], v[70:71], v[240:241] op_sel_hi:[1,0]
	v_pk_mul_f32 v[72:73], v[72:73], v[240:241] op_sel_hi:[1,0]
	v_pk_mul_f32 v[74:75], v[74:75], v[236:237] op_sel_hi:[1,0]
	v_pk_mul_f32 v[76:77], v[76:77], v[236:237] op_sel_hi:[1,0]
	v_pk_mul_f32 v[78:79], v[78:79], v[240:241] op_sel_hi:[1,0]
	v_pk_mul_f32 v[80:81], v[80:81], v[240:241] op_sel_hi:[1,0]
	v_pk_mul_f32 v[50:51], v[50:51], v[236:237] op_sel_hi:[1,0]
	v_pk_mul_f32 v[52:53], v[52:53], v[236:237] op_sel_hi:[1,0]
	v_pk_mul_f32 v[54:55], v[54:55], v[240:241] op_sel_hi:[1,0]
	v_pk_mul_f32 v[56:57], v[56:57], v[240:241] op_sel_hi:[1,0]
	v_pk_mul_f32 v[58:59], v[58:59], v[236:237] op_sel_hi:[1,0]
	v_pk_mul_f32 v[60:61], v[60:61], v[236:237] op_sel_hi:[1,0]
	v_pk_mul_f32 v[62:63], v[62:63], v[240:241] op_sel_hi:[1,0]
	v_pk_mul_f32 v[64:65], v[64:65], v[240:241] op_sel_hi:[1,0]
	v_pk_mul_f32 v[34:35], v[34:35], v[236:237] op_sel_hi:[1,0]
	v_pk_mul_f32 v[36:37], v[36:37], v[236:237] op_sel_hi:[1,0]
	v_pk_mul_f32 v[38:39], v[38:39], v[240:241] op_sel_hi:[1,0]
	v_pk_mul_f32 v[40:41], v[40:41], v[240:241] op_sel_hi:[1,0]
	v_pk_mul_f32 v[42:43], v[42:43], v[236:237] op_sel_hi:[1,0]
	v_pk_mul_f32 v[44:45], v[44:45], v[236:237] op_sel_hi:[1,0]
	v_pk_mul_f32 v[46:47], v[46:47], v[240:241] op_sel_hi:[1,0]
	v_pk_mul_f32 v[48:49], v[48:49], v[240:241] op_sel_hi:[1,0]
	v_pk_mul_f32 v[18:19], v[18:19], v[236:237] op_sel_hi:[1,0]
	v_pk_mul_f32 v[20:21], v[20:21], v[236:237] op_sel_hi:[1,0]
	v_pk_mul_f32 v[22:23], v[22:23], v[240:241] op_sel_hi:[1,0]
	v_pk_mul_f32 v[24:25], v[24:25], v[240:241] op_sel_hi:[1,0]
	v_pk_mul_f32 v[26:27], v[26:27], v[236:237] op_sel_hi:[1,0]
	v_pk_mul_f32 v[28:29], v[28:29], v[236:237] op_sel_hi:[1,0]
	v_pk_mul_f32 v[30:31], v[30:31], v[240:241] op_sel_hi:[1,0]
	v_pk_mul_f32 v[32:33], v[32:33], v[240:241] op_sel_hi:[1,0]
; #define SBAR() __builtin_amdgcn_sched_barrier(0)
; __device__ __forceinline__ int crow(int r, int hi) { return (r & 3) + 8 * (r >> 2) + 4 * hi; }
; __device__ __forceinline__ int crow(int r, int hi) { return (r & 3) + 8 * (r >> 2) + 4 * hi; }
; __device__ __forceinline__ void partialSM(f32x16& p0, f32x16& p1, float& m_reg, float& mn, float& alpha) {
;     ...
;   float mnC = -mn * C;
;   for (int r = 0; r < 16; ++r) p0[r] = fmaf(p0[r], C, mnC); for (int r = 0; r < 16; ++r) p1[r] = fmaf(p1[r], C, mnC);
;   for (int r = 0; r < 16; ++r) p0[r] = __builtin_amdgcn_exp2f(p0[r]);
; }
; __device__ __forceinline__ void finishSM(f32x16& p0, f32x16& p1, float alpha, float& l_reg, bf16x8& pa0, bf16x8& pa1, bf16x8& pa2, bf16x8& pa3) {
;   for (int r = 0; r < 16; ++r) p1[r] = __builtin_amdgcn_exp2f(p1[r]);
;   float ps = 0; for (int r = 0; r < 16; ++r) ps += p0[r]; for (int r = 0; r < 16; ++r) ps += p1[r];
;   { auto rr = __builtin_amdgcn_permlane32_swap(__float_as_uint(ps), __float_as_uint(ps), false, false);
;     ps = __uint_as_float(rr[0]) + __uint_as_float(rr[1]); }
;   l_reg = l_reg * alpha + ps;
;     ...
;   PK4(p0, 0, pa0); PK4(p0, 8, pa1); PK4(p1, 0, pa2); PK4(p1, 8, pa3);
; __device__ __forceinline__ void attn_body256(const bf16_t* __restrict__ Qb, const bf16_t* __restrict__ Kh, const bf16_t* __restrict__ Vh,
;                                              bf16_t* Ob, int seq, unsigned char* lds, float lam, int MODE, bf16_t* Ab, const float* wsub) {
;     ...
;   for (int j = 0; j < NT; ++j) {
;     const int b = j & 1;
;     f32x16 p0, p1; float mn, alpha; bf16x8 pa0, pa1, pa2, pa3;
;     SBAR(); qkt(p0, p1, (const bf16_t*)(lds + A2_KOFF + b * A2_KBUF), qr, r32, hi);
;     partialSM(p0, p1, m_reg, mn, alpha);
;     if (__any(alpha < 1.f)) { if (hi == 0) al_l[r32] = alpha; asm volatile("s_waitcnt lgkmcnt(0)" ::: "memory");
; #pragma unroll
;       for (int r = 0; r < 16; ++r) { const float a = al_l[crow(r, hi)];
; #pragma unroll
;         for (int d = 0; d < 8; ++d) o[d][r] *= a; } }
;     finishSM(p0, p1, alpha, l_reg, pa0, pa1, pa2, pa3); SBAR();
;     pv_all(o, vb0 + b * A2_VBUF, pa0, pa1, pa2, pa3);
;     asm volatile("s_waitcnt vmcnt(0)" ::: "memory"); __syncthreads();
;     if (j + 2 < NT) A2_DMA(j + 2, b);
;   }
.Lat_y_noresc:
	v_fmamk_f32 v130, v130, 0x3e0293ee, v251
	v_fmamk_f32 v131, v131, 0x3e0293ee, v251
	v_fmamk_f32 v132, v132, 0x3e0293ee, v251
	v_fmamk_f32 v133, v133, 0x3e0293ee, v251
	v_fmamk_f32 v134, v134, 0x3e0293ee, v238
	v_fmamk_f32 v135, v135, 0x3e0293ee, v238
	v_fmamk_f32 v136, v136, 0x3e0293ee, v238
	v_fmamk_f32 v137, v137, 0x3e0293ee, v238
	v_fmamk_f32 v138, v138, 0x3e0293ee, v251
	v_fmamk_f32 v139, v139, 0x3e0293ee, v251
	v_fmamk_f32 v140, v140, 0x3e0293ee, v251
	v_fmamk_f32 v141, v141, 0x3e0293ee, v251
	v_fmamk_f32 v142, v142, 0x3e0293ee, v238
	v_fmamk_f32 v143, v143, 0x3e0293ee, v238
	v_fmamk_f32 v144, v144, 0x3e0293ee, v238
	v_fmamk_f32 v145, v145, 0x3e0293ee, v238
	v_fmamk_f32 v146, v146, 0x3e0293ee, v251
	v_fmamk_f32 v147, v147, 0x3e0293ee, v251
	v_fmamk_f32 v148, v148, 0x3e0293ee, v251
	v_fmamk_f32 v149, v149, 0x3e0293ee, v251
	v_fmamk_f32 v150, v150, 0x3e0293ee, v238
	v_fmamk_f32 v151, v151, 0x3e0293ee, v238
	v_fmamk_f32 v152, v152, 0x3e0293ee, v238
	v_fmamk_f32 v153, v153, 0x3e0293ee, v238
	v_fmamk_f32 v154, v154, 0x3e0293ee, v251
	v_fmamk_f32 v155, v155, 0x3e0293ee, v251
	v_fmamk_f32 v156, v156, 0x3e0293ee, v251
	v_fmamk_f32 v157, v157, 0x3e0293ee, v251
	v_fmamk_f32 v158, v158, 0x3e0293ee, v238
	v_fmamk_f32 v159, v159, 0x3e0293ee, v238
	v_fmamk_f32 v160, v160, 0x3e0293ee, v238
	v_fmamk_f32 v161, v161, 0x3e0293ee, v238
	v_exp_f32_e32 v130, v130
	v_exp_f32_e32 v131, v131
	v_exp_f32_e32 v132, v132
	v_exp_f32_e32 v133, v133
	v_exp_f32_e32 v134, v134
	v_exp_f32_e32 v135, v135
	v_exp_f32_e32 v136, v136
	v_exp_f32_e32 v137, v137
	v_exp_f32_e32 v138, v138
	v_exp_f32_e32 v139, v139
	v_exp_f32_e32 v140, v140
	v_exp_f32_e32 v141, v141
	v_exp_f32_e32 v142, v142
	v_exp_f32_e32 v143, v143
	v_exp_f32_e32 v144, v144
	v_exp_f32_e32 v145, v145
	v_exp_f32_e32 v146, v146
	v_exp_f32_e32 v147, v147
	v_exp_f32_e32 v148, v148
	v_exp_f32_e32 v149, v149
	v_exp_f32_e32 v150, v150
	v_exp_f32_e32 v151, v151
	v_exp_f32_e32 v152, v152
	v_exp_f32_e32 v153, v153
	v_exp_f32_e32 v154, v154
	v_exp_f32_e32 v155, v155
	v_exp_f32_e32 v156, v156
	v_exp_f32_e32 v157, v157
	v_exp_f32_e32 v158, v158
	v_exp_f32_e32 v159, v159
	v_exp_f32_e32 v160, v160
	v_exp_f32_e32 v161, v161
	v_add_f32_e32 v194, v130, v131
	v_add_f32_e32 v194, v194, v132
	v_add_f32_e32 v194, v194, v133
	v_add_f32_e32 v194, v194, v138
	v_add_f32_e32 v194, v194, v139
	v_add_f32_e32 v194, v194, v140
	v_add_f32_e32 v194, v194, v141
	v_add_f32_e32 v194, v194, v146
	v_add_f32_e32 v194, v194, v147
	v_add_f32_e32 v194, v194, v148
	v_add_f32_e32 v194, v194, v149
	v_add_f32_e32 v194, v194, v154
	v_add_f32_e32 v194, v194, v155
	v_add_f32_e32 v194, v194, v156
	v_add_f32_e32 v194, v194, v157
	v_add_f32_e32 v195, v134, v135
	v_add_f32_e32 v195, v195, v136
	v_add_f32_e32 v195, v195, v137
	v_add_f32_e32 v195, v195, v142
	v_add_f32_e32 v195, v195, v143
	v_add_f32_e32 v195, v195, v144
	v_add_f32_e32 v195, v195, v145
	v_add_f32_e32 v195, v195, v150
	v_add_f32_e32 v195, v195, v151
	v_add_f32_e32 v195, v195, v152
	v_add_f32_e32 v195, v195, v153
	v_add_f32_e32 v195, v195, v158
	v_add_f32_e32 v195, v195, v159
	v_add_f32_e32 v195, v195, v160
	v_add_f32_e32 v195, v195, v161
	v_add_f32_e32 v250, v250, v194
	v_add_f32_e32 v234, v234, v195
	v_cvt_pk_bf16_f32 v130, v130, v131
	v_cvt_pk_bf16_f32 v131, v132, v133
	v_cvt_pk_bf16_f32 v132, v138, v139
	v_cvt_pk_bf16_f32 v133, v140, v141
	v_cvt_pk_bf16_f32 v134, v134, v135
	v_cvt_pk_bf16_f32 v135, v136, v137
	v_cvt_pk_bf16_f32 v136, v142, v143
	v_cvt_pk_bf16_f32 v137, v144, v145
	v_cvt_pk_bf16_f32 v138, v146, v147
	v_cvt_pk_bf16_f32 v139, v148, v149
	v_cvt_pk_bf16_f32 v140, v154, v155
	v_cvt_pk_bf16_f32 v141, v156, v157
	v_cvt_pk_bf16_f32 v142, v150, v151
	v_cvt_pk_bf16_f32 v143, v152, v153
	v_cvt_pk_bf16_f32 v144, v158, v159
	v_cvt_pk_bf16_f32 v145, v160, v161
	v_add_u32_e32 v244, s98, v248
	ds_read_b64_tr_b16 v[146:147], v244
	ds_read_b64_tr_b16 v[148:149], v244 offset:4096
	ds_read_b64_tr_b16 v[150:151], v244 offset:8192
	ds_read_b64_tr_b16 v[152:153], v244 offset:12288
	ds_read_b64_tr_b16 v[154:155], v244 offset:256
	ds_read_b64_tr_b16 v[156:157], v244 offset:4352
	ds_read_b64_tr_b16 v[158:159], v244 offset:8448
	ds_read_b64_tr_b16 v[160:161], v244 offset:12544
	ds_read_b64_tr_b16 v[194:195], v244 offset:512
	ds_read_b64_tr_b16 v[196:197], v244 offset:4608
	ds_read_b64_tr_b16 v[198:199], v244 offset:8704
	ds_read_b64_tr_b16 v[200:201], v244 offset:12800
	s_waitcnt vmcnt(0)
	s_barrier
	s_mov_b32 s101, s98
	s_mov_b32 s98, s99
	s_mov_b32 s99, s100
	s_mov_b32 s100, s101
	s_add_u32 s14, s14, 0x40000
	s_addc_u32 s15, s15, 0
	s_add_i32 s13, s13, 1
	s_cmp_eq_u32 s23, s14
	s_cbranch_scc0 .Lat_y_top
; #define SBAR() __builtin_amdgcn_sched_barrier(0)
; #define PV_STEP(B) do { pv_reads<(B) + 1>(fn, vb); asm volatile("s_waitcnt lgkmcnt(8)" ::: "memory"); SBAR(); pv_mma(o[B], fc, pa0, pa1, pa2, pa3); SBAR(); fc = fn; } while (0)
; template <int B> __device__ __forceinline__ void pv_reads(VFrag& f, int vb) {
;   constexpr int base = (B >> 2) * 16384 + (B & 3) * 512;
;   f.l0 = tr_read<base + 0 * 4096>(vb); f.h0 = tr_read<base + 0 * 4096 + 2048>(vb); f.l1 = tr_read<base + 1 * 4096>(vb); f.h1 = tr_read<base + 1 * 4096 + 2048>(vb);
;   f.l2 = tr_read<base + 2 * 4096>(vb); f.h2 = tr_read<base + 2 * 4096 + 2048>(vb); f.l3 = tr_read<base + 3 * 4096>(vb); f.h3 = tr_read<base + 3 * 4096 + 2048>(vb);
; }
; __device__ __forceinline__ void pv_mma(f32x16& od, const VFrag& f, bf16x8 pa0, bf16x8 pa1, bf16x8 pa2, bf16x8 pa3) {
;     ...
;   od = __builtin_amdgcn_mfma_f32_32x32x16_bf16(pa0, PKV(f.l0, f.h0), od, 0, 0, 0);
;   od = __builtin_amdgcn_mfma_f32_32x32x16_bf16(pa1, PKV(f.l1, f.h1), od, 0, 0, 0);
;   od = __builtin_amdgcn_mfma_f32_32x32x16_bf16(pa2, PKV(f.l2, f.h2), od, 0, 0, 0);
;   od = __builtin_amdgcn_mfma_f32_32x32x16_bf16(pa3, PKV(f.l3, f.h3), od, 0, 0, 0);
;     ...
; }
; __device__ __forceinline__ void pv_all(f32x16* o, int vb, bf16x8 pa0, bf16x8 pa1, bf16x8 pa2, bf16x8 pa3) {
;   VFrag fc, fn;
;   pv_reads<0>(fc, vb);
;   PV_STEP(0); PV_STEP(1); PV_STEP(2); PV_STEP(3); PV_STEP(4); PV_STEP(5); PV_STEP(6);
;   asm volatile("s_waitcnt lgkmcnt(0)" ::: "memory"); SBAR(); pv_mma(o[7], fc, pa0, pa1, pa2, pa3);
; }
	s_waitcnt lgkmcnt(8)
	v_mfma_f32_16x16x32_bf16 v[2:5], v[146:149], v[130:133], v[2:5]
	v_mfma_f32_16x16x32_bf16 v[6:9], v[146:149], v[134:137], v[6:9]
	v_mfma_f32_16x16x32_bf16 v[2:5], v[150:153], v[138:141], v[2:5]
	v_mfma_f32_16x16x32_bf16 v[6:9], v[150:153], v[142:145], v[6:9]
	ds_read_b64_tr_b16 v[146:147], v244 offset:768
	ds_read_b64_tr_b16 v[148:149], v244 offset:4864
	ds_read_b64_tr_b16 v[150:151], v244 offset:8960
	ds_read_b64_tr_b16 v[152:153], v244 offset:13056
	s_waitcnt lgkmcnt(8)
	v_mfma_f32_16x16x32_bf16 v[10:13], v[154:157], v[130:133], v[10:13]
	v_mfma_f32_16x16x32_bf16 v[14:17], v[154:157], v[134:137], v[14:17]
	v_mfma_f32_16x16x32_bf16 v[10:13], v[158:161], v[138:141], v[10:13]
	v_mfma_f32_16x16x32_bf16 v[14:17], v[158:161], v[142:145], v[14:17]
	ds_read_b64_tr_b16 v[154:155], v244 offset:1024
	ds_read_b64_tr_b16 v[156:157], v244 offset:5120
	ds_read_b64_tr_b16 v[158:159], v244 offset:9216
	ds_read_b64_tr_b16 v[160:161], v244 offset:13312
	s_waitcnt lgkmcnt(8)
	v_mfma_f32_16x16x32_bf16 v[114:117], v[194:197], v[130:133], v[114:117]
	v_mfma_f32_16x16x32_bf16 v[118:121], v[194:197], v[134:137], v[118:121]
	v_mfma_f32_16x16x32_bf16 v[114:117], v[198:201], v[138:141], v[114:117]
	v_mfma_f32_16x16x32_bf16 v[118:121], v[198:201], v[142:145], v[118:121]
	ds_read_b64_tr_b16 v[194:195], v244 offset:1280
	ds_read_b64_tr_b16 v[196:197], v244 offset:5376
	ds_read_b64_tr_b16 v[198:199], v244 offset:9472
	ds_read_b64_tr_b16 v[200:201], v244 offset:13568
	s_waitcnt lgkmcnt(8)
	v_mfma_f32_16x16x32_bf16 v[122:125], v[146:149], v[130:133], v[122:125]
	v_mfma_f32_16x16x32_bf16 v[126:129], v[146:149], v[134:137], v[126:129]
	v_mfma_f32_16x16x32_bf16 v[122:125], v[150:153], v[138:141], v[122:125]
	v_mfma_f32_16x16x32_bf16 v[126:129], v[150:153], v[142:145], v[126:129]
	ds_read_b64_tr_b16 v[146:147], v244 offset:1536
	ds_read_b64_tr_b16 v[148:149], v244 offset:5632
	ds_read_b64_tr_b16 v[150:151], v244 offset:9728
	ds_read_b64_tr_b16 v[152:153], v244 offset:13824
	s_waitcnt lgkmcnt(8)
	v_mfma_f32_16x16x32_bf16 v[98:101], v[154:157], v[130:133], v[98:101]
	v_mfma_f32_16x16x32_bf16 v[102:105], v[154:157], v[134:137], v[102:105]
	v_mfma_f32_16x16x32_bf16 v[98:101], v[158:161], v[138:141], v[98:101]
	v_mfma_f32_16x16x32_bf16 v[102:105], v[158:161], v[142:145], v[102:105]
	ds_read_b64_tr_b16 v[154:155], v244 offset:1792
	ds_read_b64_tr_b16 v[156:157], v244 offset:5888
	ds_read_b64_tr_b16 v[158:159], v244 offset:9984
	ds_read_b64_tr_b16 v[160:161], v244 offset:14080
	s_waitcnt lgkmcnt(8)
	v_mfma_f32_16x16x32_bf16 v[106:109], v[194:197], v[130:133], v[106:109]
	v_mfma_f32_16x16x32_bf16 v[110:113], v[194:197], v[134:137], v[110:113]
	v_mfma_f32_16x16x32_bf16 v[106:109], v[198:201], v[138:141], v[106:109]
	v_mfma_f32_16x16x32_bf16 v[110:113], v[198:201], v[142:145], v[110:113]
	ds_read_b64_tr_b16 v[194:195], v244 offset:16384
	ds_read_b64_tr_b16 v[196:197], v244 offset:20480
	ds_read_b64_tr_b16 v[198:199], v244 offset:24576
	ds_read_b64_tr_b16 v[200:201], v244 offset:28672
	s_waitcnt lgkmcnt(8)
	v_mfma_f32_16x16x32_bf16 v[82:85], v[146:149], v[130:133], v[82:85]
	v_mfma_f32_16x16x32_bf16 v[86:89], v[146:149], v[134:137], v[86:89]
	v_mfma_f32_16x16x32_bf16 v[82:85], v[150:153], v[138:141], v[82:85]
	v_mfma_f32_16x16x32_bf16 v[86:89], v[150:153], v[142:145], v[86:89]
	ds_read_b64_tr_b16 v[146:147], v244 offset:16640
	ds_read_b64_tr_b16 v[148:149], v244 offset:20736
	ds_read_b64_tr_b16 v[150:151], v244 offset:24832
	ds_read_b64_tr_b16 v[152:153], v244 offset:28928
	s_waitcnt lgkmcnt(8)
; #define SBAR() __builtin_amdgcn_sched_barrier(0)
; #define PV_STEP(B) do { pv_reads<(B) + 1>(fn, vb); asm volatile("s_waitcnt lgkmcnt(8)" ::: "memory"); SBAR(); pv_mma(o[B], fc, pa0, pa1, pa2, pa3); SBAR(); fc = fn; } while (0)
; template <int B> __device__ __forceinline__ void pv_reads(VFrag& f, int vb) {
;   constexpr int base = (B >> 2) * 16384 + (B & 3) * 512;
;   f.l0 = tr_read<base + 0 * 4096>(vb); f.h0 = tr_read<base + 0 * 4096 + 2048>(vb); f.l1 = tr_read<base + 1 * 4096>(vb); f.h1 = tr_read<base + 1 * 4096 + 2048>(vb);
;   f.l2 = tr_read<base + 2 * 4096>(vb); f.h2 = tr_read<base + 2 * 4096 + 2048>(vb); f.l3 = tr_read<base + 3 * 4096>(vb); f.h3 = tr_read<base + 3 * 4096 + 2048>(vb);
; }
; __device__ __forceinline__ void pv_mma(f32x16& od, const VFrag& f, bf16x8 pa0, bf16x8 pa1, bf16x8 pa2, bf16x8 pa3) {
;     ...
;   od = __builtin_amdgcn_mfma_f32_32x32x16_bf16(pa0, PKV(f.l0, f.h0), od, 0, 0, 0);
;   od = __builtin_amdgcn_mfma_f32_32x32x16_bf16(pa1, PKV(f.l1, f.h1), od, 0, 0, 0);
;   od = __builtin_amdgcn_mfma_f32_32x32x16_bf16(pa2, PKV(f.l2, f.h2), od, 0, 0, 0);
;   od = __builtin_amdgcn_mfma_f32_32x32x16_bf16(pa3, PKV(f.l3, f.h3), od, 0, 0, 0);
;     ...
; }
; __device__ __forceinline__ void pv_all(f32x16* o, int vb, bf16x8 pa0, bf16x8 pa1, bf16x8 pa2, bf16x8 pa3) {
;   VFrag fc, fn;
;   pv_reads<0>(fc, vb);
;   PV_STEP(0); PV_STEP(1); PV_STEP(2); PV_STEP(3); PV_STEP(4); PV_STEP(5); PV_STEP(6);
;   asm volatile("s_waitcnt lgkmcnt(0)" ::: "memory"); SBAR(); pv_mma(o[7], fc, pa0, pa1, pa2, pa3);
; }
	v_mfma_f32_16x16x32_bf16 v[90:93], v[154:157], v[130:133], v[90:93]
	v_mfma_f32_16x16x32_bf16 v[94:97], v[154:157], v[134:137], v[94:97]
	v_mfma_f32_16x16x32_bf16 v[90:93], v[158:161], v[138:141], v[90:93]
	v_mfma_f32_16x16x32_bf16 v[94:97], v[158:161], v[142:145], v[94:97]
	ds_read_b64_tr_b16 v[154:155], v244 offset:16896
	ds_read_b64_tr_b16 v[156:157], v244 offset:20992
	ds_read_b64_tr_b16 v[158:159], v244 offset:25088
	ds_read_b64_tr_b16 v[160:161], v244 offset:29184
	s_waitcnt lgkmcnt(8)
	v_mfma_f32_16x16x32_bf16 v[66:69], v[194:197], v[130:133], v[66:69]
	v_mfma_f32_16x16x32_bf16 v[70:73], v[194:197], v[134:137], v[70:73]
	v_mfma_f32_16x16x32_bf16 v[66:69], v[198:201], v[138:141], v[66:69]
	v_mfma_f32_16x16x32_bf16 v[70:73], v[198:201], v[142:145], v[70:73]
	ds_read_b64_tr_b16 v[194:195], v244 offset:17152
	ds_read_b64_tr_b16 v[196:197], v244 offset:21248
	ds_read_b64_tr_b16 v[198:199], v244 offset:25344
	ds_read_b64_tr_b16 v[200:201], v244 offset:29440
	s_waitcnt lgkmcnt(8)
	v_mfma_f32_16x16x32_bf16 v[74:77], v[146:149], v[130:133], v[74:77]
	v_mfma_f32_16x16x32_bf16 v[78:81], v[146:149], v[134:137], v[78:81]
	v_mfma_f32_16x16x32_bf16 v[74:77], v[150:153], v[138:141], v[74:77]
	v_mfma_f32_16x16x32_bf16 v[78:81], v[150:153], v[142:145], v[78:81]
	ds_read_b64_tr_b16 v[146:147], v244 offset:17408
	ds_read_b64_tr_b16 v[148:149], v244 offset:21504
	ds_read_b64_tr_b16 v[150:151], v244 offset:25600
	ds_read_b64_tr_b16 v[152:153], v244 offset:29696
	s_waitcnt lgkmcnt(8)
	v_mfma_f32_16x16x32_bf16 v[50:53], v[154:157], v[130:133], v[50:53]
	v_mfma_f32_16x16x32_bf16 v[54:57], v[154:157], v[134:137], v[54:57]
	v_mfma_f32_16x16x32_bf16 v[50:53], v[158:161], v[138:141], v[50:53]
	v_mfma_f32_16x16x32_bf16 v[54:57], v[158:161], v[142:145], v[54:57]
	ds_read_b64_tr_b16 v[154:155], v244 offset:17664
	ds_read_b64_tr_b16 v[156:157], v244 offset:21760
	ds_read_b64_tr_b16 v[158:159], v244 offset:25856
	ds_read_b64_tr_b16 v[160:161], v244 offset:29952
	s_waitcnt lgkmcnt(8)
	v_mfma_f32_16x16x32_bf16 v[58:61], v[194:197], v[130:133], v[58:61]
	v_mfma_f32_16x16x32_bf16 v[62:65], v[194:197], v[134:137], v[62:65]
	v_mfma_f32_16x16x32_bf16 v[58:61], v[198:201], v[138:141], v[58:61]
	v_mfma_f32_16x16x32_bf16 v[62:65], v[198:201], v[142:145], v[62:65]
	ds_read_b64_tr_b16 v[194:195], v244 offset:17920
	ds_read_b64_tr_b16 v[196:197], v244 offset:22016
	ds_read_b64_tr_b16 v[198:199], v244 offset:26112
	ds_read_b64_tr_b16 v[200:201], v244 offset:30208
	s_waitcnt lgkmcnt(8)
	v_mfma_f32_16x16x32_bf16 v[34:37], v[146:149], v[130:133], v[34:37]
	v_mfma_f32_16x16x32_bf16 v[38:41], v[146:149], v[134:137], v[38:41]
	v_mfma_f32_16x16x32_bf16 v[34:37], v[150:153], v[138:141], v[34:37]
	v_mfma_f32_16x16x32_bf16 v[38:41], v[150:153], v[142:145], v[38:41]
	ds_read_b64_tr_b16 v[146:147], v244 offset:18176
	ds_read_b64_tr_b16 v[148:149], v244 offset:22272
	ds_read_b64_tr_b16 v[150:151], v244 offset:26368
	ds_read_b64_tr_b16 v[152:153], v244 offset:30464
	s_waitcnt lgkmcnt(8)
	v_mfma_f32_16x16x32_bf16 v[42:45], v[154:157], v[130:133], v[42:45]
	v_mfma_f32_16x16x32_bf16 v[46:49], v[154:157], v[134:137], v[46:49]
	v_mfma_f32_16x16x32_bf16 v[42:45], v[158:161], v[138:141], v[42:45]
	v_mfma_f32_16x16x32_bf16 v[46:49], v[158:161], v[142:145], v[46:49]
	s_waitcnt lgkmcnt(4)
	v_mfma_f32_16x16x32_bf16 v[18:21], v[194:197], v[130:133], v[18:21]
	v_mfma_f32_16x16x32_bf16 v[22:25], v[194:197], v[134:137], v[22:25]
	v_mfma_f32_16x16x32_bf16 v[18:21], v[198:201], v[138:141], v[18:21]
	v_mfma_f32_16x16x32_bf16 v[22:25], v[198:201], v[142:145], v[22:25]
	s_waitcnt lgkmcnt(0)
	v_mfma_f32_16x16x32_bf16 v[26:29], v[146:149], v[130:133], v[26:29]
	v_mfma_f32_16x16x32_bf16 v[30:33], v[146:149], v[134:137], v[30:33]
	v_mfma_f32_16x16x32_bf16 v[26:29], v[150:153], v[138:141], v[26:29]
	v_mfma_f32_16x16x32_bf16 v[30:33], v[150:153], v[142:145], v[30:33]
